# v22 + snake MFMA order in all GEMM K-loops (consecutive MFMAs share one operand register)
# speedup vs baseline: 1.0009x; 1.0009x over previous
.LBB0_133:
	ds_read_b128 v[150:153], v156
	ds_read_b128 v[160:163], v156 offset:1024
	ds_read_b128 v[164:167], v156 offset:2048
	ds_read_b128 v[168:171], v156 offset:3072
	ds_read_b128 v[176:179], v157
	ds_read_b128 v[180:183], v157 offset:1024
	ds_read_b128 v[184:187], v157 offset:2048
	ds_read_b128 v[188:191], v157 offset:3072
	s_add_u32 s20, s4, 0xfff00080
	s_addc_u32 s21, s5, -1
	s_cmp_eq_u32 s47, 60
	s_cselect_b32 s23, s13, s21
	s_cselect_b32 s22, s43, s20
	s_cselect_b32 s21, s11, s46
	s_cselect_b32 s20, s44, s45
	v_lshl_add_u64 v[172:173], s[4:5], 0, v[142:143]
	s_add_i32 m0, s19, 0xc000
	ds_read_b128 v[192:195], v158
	ds_read_b128 v[196:199], v158 offset:1024
	ds_read_b128 v[200:203], v158 offset:2048
	ds_read_b128 v[204:207], v158 offset:3072
	ds_read_b128 v[208:211], v158 offset:4096
	ds_read_b128 v[212:215], v158 offset:5120
	ds_read_b128 v[216:219], v158 offset:6144
	ds_read_b128 v[220:223], v158 offset:7168
	global_load_lds_dwordx4 v[172:173], off
	v_lshl_add_u64 v[172:173], s[4:5], 0, v[144:145]
	s_add_i32 m0, s19, 0xe000
	s_nop 0
	global_load_lds_dwordx4 v[172:173], off
	s_waitcnt vmcnt(8)
	s_waitcnt lgkmcnt(0)
	s_barrier
	s_setprio 1
	s_waitcnt lgkmcnt(0)
	v_mfma_f32_16x16x32_bf16 v[126:129], v[150:153], v[192:195], v[126:129]
	v_mfma_f32_16x16x32_bf16 v[122:125], v[164:167], v[192:195], v[122:125]
	v_mfma_f32_16x16x32_bf16 v[110:113], v[164:167], v[200:203], v[110:113]
	v_mfma_f32_16x16x32_bf16 v[118:121], v[150:153], v[200:203], v[118:121]
	v_mfma_f32_16x16x32_bf16 v[102:105], v[150:153], v[208:211], v[102:105]
	v_mfma_f32_16x16x32_bf16 v[94:97], v[164:167], v[208:211], v[94:97]
	v_mfma_f32_16x16x32_bf16 v[78:81], v[164:167], v[216:219], v[78:81]
	v_mfma_f32_16x16x32_bf16 v[86:89], v[150:153], v[216:219], v[86:89]
	v_mfma_f32_16x16x32_bf16 v[126:129], v[160:163], v[196:199], v[126:129]
	v_mfma_f32_16x16x32_bf16 v[122:125], v[168:171], v[196:199], v[122:125]
	v_mfma_f32_16x16x32_bf16 v[110:113], v[168:171], v[204:207], v[110:113]
	v_mfma_f32_16x16x32_bf16 v[118:121], v[160:163], v[204:207], v[118:121]
	v_mfma_f32_16x16x32_bf16 v[102:105], v[160:163], v[212:215], v[102:105]
	v_mfma_f32_16x16x32_bf16 v[94:97], v[168:171], v[212:215], v[94:97]
	v_mfma_f32_16x16x32_bf16 v[78:81], v[168:171], v[220:223], v[78:81]
	v_mfma_f32_16x16x32_bf16 v[86:89], v[160:163], v[220:223], v[86:89]
	s_setprio 0
	s_setprio 1
	v_mfma_f32_16x16x32_bf16 v[114:117], v[176:179], v[192:195], v[114:117]
	v_mfma_f32_16x16x32_bf16 v[106:109], v[184:187], v[192:195], v[106:109]
	v_mfma_f32_16x16x32_bf16 v[90:93], v[184:187], v[200:203], v[90:93]
	v_mfma_f32_16x16x32_bf16 v[98:101], v[176:179], v[200:203], v[98:101]
	v_mfma_f32_16x16x32_bf16 v[82:85], v[176:179], v[208:211], v[82:85]
	v_mfma_f32_16x16x32_bf16 v[74:77], v[184:187], v[208:211], v[74:77]
	v_mfma_f32_16x16x32_bf16 v[66:69], v[184:187], v[216:219], v[66:69]
	v_mfma_f32_16x16x32_bf16 v[70:73], v[176:179], v[216:219], v[70:73]
	v_mfma_f32_16x16x32_bf16 v[114:117], v[180:183], v[196:199], v[114:117]
	v_mfma_f32_16x16x32_bf16 v[106:109], v[188:191], v[196:199], v[106:109]
	v_mfma_f32_16x16x32_bf16 v[90:93], v[188:191], v[204:207], v[90:93]
	v_mfma_f32_16x16x32_bf16 v[98:101], v[180:183], v[204:207], v[98:101]
	v_mfma_f32_16x16x32_bf16 v[82:85], v[180:183], v[212:215], v[82:85]
	v_mfma_f32_16x16x32_bf16 v[74:77], v[188:191], v[212:215], v[74:77]
	v_mfma_f32_16x16x32_bf16 v[66:69], v[188:191], v[220:223], v[66:69]
	v_mfma_f32_16x16x32_bf16 v[70:73], v[180:183], v[220:223], v[70:73]
	s_setprio 0
	s_barrier
	s_add_i32 s48, s39, s29
	v_lshl_add_u64 v[172:173], s[20:21], 0, v[132:133]
	s_mov_b32 m0, s48
	ds_read_b128 v[192:195], v158 offset:16384
	ds_read_b128 v[196:199], v158 offset:17408
	ds_read_b128 v[200:203], v158 offset:18432
	ds_read_b128 v[204:207], v158 offset:19456
	ds_read_b128 v[208:211], v158 offset:20480
	ds_read_b128 v[212:215], v158 offset:21504
	ds_read_b128 v[216:219], v158 offset:22528
	ds_read_b128 v[220:223], v158 offset:23552
	global_load_lds_dwordx4 v[172:173], off
	s_add_i32 m0, s48, 0x2000
	s_add_u32 s48, s20, 0x100000
	v_lshl_add_u64 v[224:225], s[20:21], 0, v[136:137]
	s_addc_u32 s49, s21, 0
	s_add_i32 s50, s40, s29
	global_load_lds_dwordx4 v[224:225], off
	v_lshl_add_u64 v[226:227], s[48:49], 0, v[132:133]
	s_mov_b32 m0, s50
	v_lshl_add_u64 v[228:229], s[22:23], 0, v[134:135]
	global_load_lds_dwordx4 v[226:227], off
	v_lshl_add_u64 v[226:227], s[48:49], 0, v[136:137]
	s_add_i32 m0, s50, 0x2000
	s_nop 0
	global_load_lds_dwordx4 v[226:227], off
	v_lshl_add_u64 v[226:227], s[22:23], 0, v[130:131]
	s_mov_b32 m0, s19
	s_nop 0
	global_load_lds_dwordx4 v[226:227], off
	s_mov_b32 m0, s30
	s_nop 0
	global_load_lds_dwordx4 v[228:229], off
	s_waitcnt vmcnt(8)
	s_waitcnt lgkmcnt(0)
	s_barrier
	s_setprio 1
	s_waitcnt lgkmcnt(0)
	v_mfma_f32_16x16x32_bf16 v[62:65], v[150:153], v[192:195], v[62:65]
	v_mfma_f32_16x16x32_bf16 v[58:61], v[164:167], v[192:195], v[58:61]
	v_mfma_f32_16x16x32_bf16 v[46:49], v[164:167], v[200:203], v[46:49]
	v_mfma_f32_16x16x32_bf16 v[54:57], v[150:153], v[200:203], v[54:57]
	v_mfma_f32_16x16x32_bf16 v[38:41], v[150:153], v[208:211], v[38:41]
	v_mfma_f32_16x16x32_bf16 v[30:33], v[164:167], v[208:211], v[30:33]
	v_mfma_f32_16x16x32_bf16 v[14:17], v[164:167], v[216:219], v[14:17]
	v_mfma_f32_16x16x32_bf16 v[22:25], v[150:153], v[216:219], v[22:25]
	v_mfma_f32_16x16x32_bf16 v[62:65], v[160:163], v[196:199], v[62:65]
	v_mfma_f32_16x16x32_bf16 v[58:61], v[168:171], v[196:199], v[58:61]
	v_mfma_f32_16x16x32_bf16 v[46:49], v[168:171], v[204:207], v[46:49]
	v_mfma_f32_16x16x32_bf16 v[54:57], v[160:163], v[204:207], v[54:57]
	v_mfma_f32_16x16x32_bf16 v[38:41], v[160:163], v[212:215], v[38:41]
	v_mfma_f32_16x16x32_bf16 v[30:33], v[168:171], v[212:215], v[30:33]
	v_mfma_f32_16x16x32_bf16 v[14:17], v[168:171], v[220:223], v[14:17]
	v_mfma_f32_16x16x32_bf16 v[22:25], v[160:163], v[220:223], v[22:25]
	s_setprio 0
	s_setprio 1
	v_mfma_f32_16x16x32_bf16 v[50:53], v[176:179], v[192:195], v[50:53]
	v_mfma_f32_16x16x32_bf16 v[42:45], v[184:187], v[192:195], v[42:45]
	v_mfma_f32_16x16x32_bf16 v[26:29], v[184:187], v[200:203], v[26:29]
	v_mfma_f32_16x16x32_bf16 v[34:37], v[176:179], v[200:203], v[34:37]
	v_mfma_f32_16x16x32_bf16 v[18:21], v[176:179], v[208:211], v[18:21]
	v_mfma_f32_16x16x32_bf16 v[10:13], v[184:187], v[208:211], v[10:13]
	v_mfma_f32_16x16x32_bf16 v[2:5], v[184:187], v[216:219], v[2:5]
	v_mfma_f32_16x16x32_bf16 v[6:9], v[176:179], v[216:219], v[6:9]
	v_mfma_f32_16x16x32_bf16 v[50:53], v[180:183], v[196:199], v[50:53]
	v_mfma_f32_16x16x32_bf16 v[42:45], v[188:191], v[196:199], v[42:45]
	v_mfma_f32_16x16x32_bf16 v[26:29], v[188:191], v[204:207], v[26:29]
	v_mfma_f32_16x16x32_bf16 v[34:37], v[180:183], v[204:207], v[34:37]
	v_mfma_f32_16x16x32_bf16 v[18:21], v[180:183], v[212:215], v[18:21]
	v_mfma_f32_16x16x32_bf16 v[10:13], v[188:191], v[212:215], v[10:13]
	v_mfma_f32_16x16x32_bf16 v[2:5], v[188:191], v[220:223], v[2:5]
	v_mfma_f32_16x16x32_bf16 v[6:9], v[180:183], v[220:223], v[6:9]
	s_setprio 0
	s_barrier
	s_add_i32 s48, 0, 0x18000
	v_add_u32_e32 v159, s48, v154
	s_add_i32 s49, 0, 0x1c000
	ds_read_b128 v[150:153], v159
	ds_read_b128 v[160:163], v159 offset:1024
	ds_read_b128 v[164:167], v159 offset:2048
	ds_read_b128 v[168:171], v159 offset:3072
	v_add_u32_e32 v159, s49, v154
	ds_read_b128 v[176:179], v159
	ds_read_b128 v[180:183], v159 offset:1024
	ds_read_b128 v[184:187], v159 offset:2048
	ds_read_b128 v[188:191], v159 offset:3072
	s_add_u32 s22, s22, 0x100000
	s_addc_u32 s23, s23, 0
	s_mov_b32 m0, s31
	v_lshl_add_u64 v[230:231], s[22:23], 0, v[130:131]
	ds_read_b128 v[192:195], v158 offset:32768
	ds_read_b128 v[196:199], v158 offset:33792
	ds_read_b128 v[200:203], v158 offset:34816
	ds_read_b128 v[204:207], v158 offset:35840
	ds_read_b128 v[208:211], v158 offset:36864
	ds_read_b128 v[212:215], v158 offset:37888
	ds_read_b128 v[216:219], v158 offset:38912
	ds_read_b128 v[220:223], v158 offset:39936
	global_load_lds_dwordx4 v[230:231], off
	v_lshl_add_u64 v[230:231], s[22:23], 0, v[134:135]
	s_mov_b32 m0, s33
	s_nop 0
	global_load_lds_dwordx4 v[230:231], off
	s_waitcnt vmcnt(8)
	s_waitcnt lgkmcnt(0)
	s_barrier
	s_setprio 1
	s_waitcnt lgkmcnt(0)
	v_mfma_f32_16x16x32_bf16 v[126:129], v[150:153], v[192:195], v[126:129]
	v_mfma_f32_16x16x32_bf16 v[122:125], v[164:167], v[192:195], v[122:125]
	v_mfma_f32_16x16x32_bf16 v[110:113], v[164:167], v[200:203], v[110:113]
	v_mfma_f32_16x16x32_bf16 v[118:121], v[150:153], v[200:203], v[118:121]
	v_mfma_f32_16x16x32_bf16 v[102:105], v[150:153], v[208:211], v[102:105]
	v_mfma_f32_16x16x32_bf16 v[94:97], v[164:167], v[208:211], v[94:97]
	v_mfma_f32_16x16x32_bf16 v[78:81], v[164:167], v[216:219], v[78:81]
	v_mfma_f32_16x16x32_bf16 v[86:89], v[150:153], v[216:219], v[86:89]
	v_mfma_f32_16x16x32_bf16 v[126:129], v[160:163], v[196:199], v[126:129]
	v_mfma_f32_16x16x32_bf16 v[122:125], v[168:171], v[196:199], v[122:125]
	v_mfma_f32_16x16x32_bf16 v[110:113], v[168:171], v[204:207], v[110:113]
	v_mfma_f32_16x16x32_bf16 v[118:121], v[160:163], v[204:207], v[118:121]
	v_mfma_f32_16x16x32_bf16 v[102:105], v[160:163], v[212:215], v[102:105]
	v_mfma_f32_16x16x32_bf16 v[94:97], v[168:171], v[212:215], v[94:97]
	v_mfma_f32_16x16x32_bf16 v[78:81], v[168:171], v[220:223], v[78:81]
	v_mfma_f32_16x16x32_bf16 v[86:89], v[160:163], v[220:223], v[86:89]
	s_setprio 0
	s_setprio 1
	v_mfma_f32_16x16x32_bf16 v[114:117], v[176:179], v[192:195], v[114:117]
	v_mfma_f32_16x16x32_bf16 v[106:109], v[184:187], v[192:195], v[106:109]
	v_mfma_f32_16x16x32_bf16 v[90:93], v[184:187], v[200:203], v[90:93]
	v_mfma_f32_16x16x32_bf16 v[98:101], v[176:179], v[200:203], v[98:101]
	v_mfma_f32_16x16x32_bf16 v[82:85], v[176:179], v[208:211], v[82:85]
	v_mfma_f32_16x16x32_bf16 v[74:77], v[184:187], v[208:211], v[74:77]
	v_mfma_f32_16x16x32_bf16 v[66:69], v[184:187], v[216:219], v[66:69]
	v_mfma_f32_16x16x32_bf16 v[70:73], v[176:179], v[216:219], v[70:73]
	v_mfma_f32_16x16x32_bf16 v[114:117], v[180:183], v[196:199], v[114:117]
	v_mfma_f32_16x16x32_bf16 v[106:109], v[188:191], v[196:199], v[106:109]
	v_mfma_f32_16x16x32_bf16 v[90:93], v[188:191], v[204:207], v[90:93]
	v_mfma_f32_16x16x32_bf16 v[98:101], v[180:183], v[204:207], v[98:101]
	v_mfma_f32_16x16x32_bf16 v[82:85], v[180:183], v[212:215], v[82:85]
	v_mfma_f32_16x16x32_bf16 v[74:77], v[188:191], v[212:215], v[74:77]
	v_mfma_f32_16x16x32_bf16 v[66:69], v[188:191], v[220:223], v[66:69]
	v_mfma_f32_16x16x32_bf16 v[70:73], v[180:183], v[220:223], v[70:73]
	s_setprio 0
	s_barrier
	s_add_i32 s22, s48, s29
	v_lshl_add_u64 v[172:173], v[172:173], 0, s[2:3]
	s_mov_b32 m0, s22
	ds_read_b128 v[192:195], v158 offset:49152
	ds_read_b128 v[196:199], v158 offset:50176
	ds_read_b128 v[200:203], v158 offset:51200
	ds_read_b128 v[204:207], v158 offset:52224
	ds_read_b128 v[208:211], v158 offset:53248
	ds_read_b128 v[212:215], v158 offset:54272
	ds_read_b128 v[216:219], v158 offset:55296
	ds_read_b128 v[220:223], v158 offset:56320
	global_load_lds_dwordx4 v[172:173], off
	s_add_i32 m0, s22, 0x2000
	s_add_u32 s20, s20, 0x100080
	v_lshl_add_u64 v[172:173], v[224:225], 0, s[2:3]
	s_addc_u32 s21, s21, 0
	s_add_i32 s22, s49, s29
	global_load_lds_dwordx4 v[172:173], off
	v_lshl_add_u64 v[172:173], s[20:21], 0, v[132:133]
	s_mov_b32 m0, s22
	s_nop 0
	global_load_lds_dwordx4 v[172:173], off
	v_lshl_add_u64 v[172:173], s[20:21], 0, v[136:137]
	s_add_i32 m0, s22, 0x2000
	s_nop 0
	global_load_lds_dwordx4 v[172:173], off
	v_lshl_add_u64 v[172:173], v[226:227], 0, s[2:3]
	s_mov_b32 m0, s35
	s_nop 0
	global_load_lds_dwordx4 v[172:173], off
	v_lshl_add_u64 v[172:173], v[228:229], 0, s[2:3]
	s_mov_b32 m0, s36
	s_nop 0
	global_load_lds_dwordx4 v[172:173], off
	s_waitcnt vmcnt(8)
	s_waitcnt lgkmcnt(0)
	s_barrier
	s_setprio 1
	s_waitcnt lgkmcnt(0)
	v_mfma_f32_16x16x32_bf16 v[62:65], v[150:153], v[192:195], v[62:65]
	v_mfma_f32_16x16x32_bf16 v[58:61], v[164:167], v[192:195], v[58:61]
	v_mfma_f32_16x16x32_bf16 v[46:49], v[164:167], v[200:203], v[46:49]
	v_mfma_f32_16x16x32_bf16 v[54:57], v[150:153], v[200:203], v[54:57]
	v_mfma_f32_16x16x32_bf16 v[38:41], v[150:153], v[208:211], v[38:41]
	v_mfma_f32_16x16x32_bf16 v[30:33], v[164:167], v[208:211], v[30:33]
	v_mfma_f32_16x16x32_bf16 v[14:17], v[164:167], v[216:219], v[14:17]
	v_mfma_f32_16x16x32_bf16 v[22:25], v[150:153], v[216:219], v[22:25]
	v_mfma_f32_16x16x32_bf16 v[62:65], v[160:163], v[196:199], v[62:65]
	v_mfma_f32_16x16x32_bf16 v[58:61], v[168:171], v[196:199], v[58:61]
	v_mfma_f32_16x16x32_bf16 v[46:49], v[168:171], v[204:207], v[46:49]
	v_mfma_f32_16x16x32_bf16 v[54:57], v[160:163], v[204:207], v[54:57]
	v_mfma_f32_16x16x32_bf16 v[38:41], v[160:163], v[212:215], v[38:41]
	v_mfma_f32_16x16x32_bf16 v[30:33], v[168:171], v[212:215], v[30:33]
	v_mfma_f32_16x16x32_bf16 v[14:17], v[168:171], v[220:223], v[14:17]
	v_mfma_f32_16x16x32_bf16 v[22:25], v[160:163], v[220:223], v[22:25]
	s_setprio 0
	s_setprio 1
	v_mfma_f32_16x16x32_bf16 v[50:53], v[176:179], v[192:195], v[50:53]
	v_mfma_f32_16x16x32_bf16 v[42:45], v[184:187], v[192:195], v[42:45]
	v_mfma_f32_16x16x32_bf16 v[26:29], v[184:187], v[200:203], v[26:29]
	v_mfma_f32_16x16x32_bf16 v[34:37], v[176:179], v[200:203], v[34:37]
	v_mfma_f32_16x16x32_bf16 v[18:21], v[176:179], v[208:211], v[18:21]
	v_mfma_f32_16x16x32_bf16 v[10:13], v[184:187], v[208:211], v[10:13]
	v_mfma_f32_16x16x32_bf16 v[2:5], v[184:187], v[216:219], v[2:5]
	v_mfma_f32_16x16x32_bf16 v[6:9], v[176:179], v[216:219], v[6:9]
	v_mfma_f32_16x16x32_bf16 v[50:53], v[180:183], v[196:199], v[50:53]
	v_mfma_f32_16x16x32_bf16 v[42:45], v[188:191], v[196:199], v[42:45]
	v_mfma_f32_16x16x32_bf16 v[26:29], v[188:191], v[204:207], v[26:29]
	v_mfma_f32_16x16x32_bf16 v[34:37], v[180:183], v[204:207], v[34:37]
	v_mfma_f32_16x16x32_bf16 v[18:21], v[180:183], v[212:215], v[18:21]
	v_mfma_f32_16x16x32_bf16 v[10:13], v[188:191], v[212:215], v[10:13]
	v_mfma_f32_16x16x32_bf16 v[2:5], v[188:191], v[220:223], v[2:5]
	v_mfma_f32_16x16x32_bf16 v[6:9], v[180:183], v[220:223], v[6:9]
	s_setprio 0
	s_barrier
	s_add_i32 s47, s47, 2
	s_add_u32 s4, s4, 0x100
	s_addc_u32 s5, s5, 0
	s_add_u32 s45, s45, 0x100
	s_addc_u32 s46, s46, 0
	s_cmp_gt_u32 s47, 61
	s_cbranch_scc0 .LBB0_133
	v_lshl_add_u32 v150, s18, 8, v1
	s_cmp_gt_i32 s42, 7
	s_mov_b64 s[4:5], -1
	s_cbranch_scc0 .LBB0_142
	s_cmp_gt_u32 s42, 31
	s_cbranch_scc0 .LBB0_139
	s_andn2_b64 vcc, exec, s[8:9]
	s_cbranch_vccnz .LBB0_138
	v_or_b32_e32 v160, 16, v150
	v_ashrrev_i32_e32 v151, 31, v150
	v_ashrrev_i32_e32 v161, 31, v160
	v_lshlrev_b64 v[152:153], 7, v[150:151]
	v_lshlrev_b64 v[160:161], 7, v[160:161]
	v_lshl_add_u64 v[152:153], v[138:139], 0, v[152:153]
	v_lshl_add_u64 v[160:161], v[138:139], 0, v[160:161]
	global_store_dwordx4 v[152:153], v[126:129], off
	global_store_dwordx4 v[152:153], v[122:125], off offset:16
	global_store_dwordx4 v[160:161], v[118:121], off
	global_store_dwordx4 v[160:161], v[110:113], off offset:16
	v_or_b32_e32 v160, 32, v150
	v_ashrrev_i32_e32 v161, 31, v160
	v_lshlrev_b64 v[160:161], 7, v[160:161]
	v_lshl_add_u64 v[160:161], v[138:139], 0, v[160:161]
	global_store_dwordx4 v[160:161], v[102:105], off
	global_store_dwordx4 v[160:161], v[94:97], off offset:16
	v_or_b32_e32 v160, 48, v150
	v_ashrrev_i32_e32 v161, 31, v160
	v_lshlrev_b64 v[160:161], 7, v[160:161]
	v_lshl_add_u64 v[160:161], v[138:139], 0, v[160:161]
	s_mov_b64 s[4:5], 0x4000
	global_store_dwordx4 v[160:161], v[86:89], off
	global_store_dwordx4 v[160:161], v[78:81], off offset:16
	v_lshl_add_u64 v[160:161], v[152:153], 0, s[4:5]
	s_movk_i32 s4, 0x4000
	v_add_co_u32_e32 v162, vcc, s4, v152
	s_mov_b64 s[4:5], 0x4800
	s_nop 0
	v_addc_co_u32_e32 v163, vcc, 0, v153, vcc
	global_store_dwordx4 v[162:163], v[62:65], off
	global_store_dwordx4 v[160:161], v[58:61], off offset:16
	v_lshl_add_u64 v[160:161], v[152:153], 0, s[4:5]
	global_store_dwordx4 v[162:163], v[54:57], off offset:2048
	global_store_dwordx4 v[160:161], v[46:49], off offset:16
	s_mov_b64 s[4:5], 0x5000
	v_add_co_u32_e32 v162, vcc, 0x5000, v152
	v_lshl_add_u64 v[160:161], v[152:153], 0, s[4:5]
	s_nop 0
	v_addc_co_u32_e32 v163, vcc, 0, v153, vcc
	s_mov_b64 s[4:5], 0x5800
	global_store_dwordx4 v[162:163], v[38:41], off
	global_store_dwordx4 v[160:161], v[30:33], off offset:16
	v_lshl_add_u64 v[152:153], v[152:153], 0, s[4:5]
	global_store_dwordx4 v[162:163], v[22:25], off offset:2048
	global_store_dwordx4 v[152:153], v[14:17], off offset:16

.LBB0_508:
	ds_read_b128 v[58:61], v168
	ds_read_b128 v[62:65], v168 offset:1024
	ds_read_b128 v[74:77], v168 offset:2048
	ds_read_b128 v[78:81], v168 offset:3072
	ds_read_b128 v[162:165], v169
	ds_read_b128 v[176:179], v169 offset:1024
	ds_read_b128 v[180:183], v169 offset:2048
	ds_read_b128 v[184:187], v169 offset:3072
	s_add_u32 s20, s0, 0xfff80080
	s_addc_u32 s21, s1, -1
	s_cmp_eq_u32 s44, 28
	s_cselect_b32 s23, s17, s21
	s_cselect_b32 s22, s40, s20
	s_cselect_b32 s21, s3, s43
	s_cselect_b32 s20, s41, s42
	v_lshl_add_u64 v[172:173], s[0:1], 0, v[154:155]
	s_add_i32 m0, s19, 0xc000
	ds_read_b128 v[188:191], v170
	ds_read_b128 v[192:195], v170 offset:1024
	ds_read_b128 v[196:199], v170 offset:2048
	ds_read_b128 v[200:203], v170 offset:3072
	ds_read_b128 v[204:207], v170 offset:4096
	ds_read_b128 v[208:211], v170 offset:5120
	ds_read_b128 v[212:215], v170 offset:6144
	ds_read_b128 v[216:219], v170 offset:7168
	global_load_lds_dwordx4 v[172:173], off
	v_lshl_add_u64 v[172:173], s[0:1], 0, v[156:157]
	s_add_i32 m0, s19, 0xe000
	s_nop 0
	global_load_lds_dwordx4 v[172:173], off
	s_waitcnt vmcnt(8)
	s_waitcnt lgkmcnt(0)
	s_barrier
	s_setprio 1
	s_waitcnt lgkmcnt(0)
	v_mfma_f32_16x16x32_bf16 v[142:145], v[58:61], v[188:191], v[142:145]
	v_mfma_f32_16x16x32_bf16 v[138:141], v[74:77], v[188:191], v[138:141]
	v_mfma_f32_16x16x32_bf16 v[122:125], v[74:77], v[196:199], v[122:125]
	v_mfma_f32_16x16x32_bf16 v[126:129], v[58:61], v[196:199], v[126:129]
	v_mfma_f32_16x16x32_bf16 v[110:113], v[58:61], v[204:207], v[110:113]
	v_mfma_f32_16x16x32_bf16 v[106:109], v[74:77], v[204:207], v[106:109]
	v_mfma_f32_16x16x32_bf16 v[90:93], v[74:77], v[212:215], v[90:93]
	v_mfma_f32_16x16x32_bf16 v[94:97], v[58:61], v[212:215], v[94:97]
	v_mfma_f32_16x16x32_bf16 v[142:145], v[62:65], v[192:195], v[142:145]
	v_mfma_f32_16x16x32_bf16 v[138:141], v[78:81], v[192:195], v[138:141]
	v_mfma_f32_16x16x32_bf16 v[122:125], v[78:81], v[200:203], v[122:125]
	v_mfma_f32_16x16x32_bf16 v[126:129], v[62:65], v[200:203], v[126:129]
	v_mfma_f32_16x16x32_bf16 v[110:113], v[62:65], v[208:211], v[110:113]
	v_mfma_f32_16x16x32_bf16 v[106:109], v[78:81], v[208:211], v[106:109]
	v_mfma_f32_16x16x32_bf16 v[90:93], v[78:81], v[216:219], v[90:93]
	v_mfma_f32_16x16x32_bf16 v[94:97], v[62:65], v[216:219], v[94:97]
	s_setprio 0
	s_setprio 1
	v_mfma_f32_16x16x32_bf16 v[134:137], v[162:165], v[188:191], v[134:137]
	v_mfma_f32_16x16x32_bf16 v[130:133], v[180:183], v[188:191], v[130:133]
	v_mfma_f32_16x16x32_bf16 v[114:117], v[180:183], v[196:199], v[114:117]
	v_mfma_f32_16x16x32_bf16 v[118:121], v[162:165], v[196:199], v[118:121]
	v_mfma_f32_16x16x32_bf16 v[102:105], v[162:165], v[204:207], v[102:105]
	v_mfma_f32_16x16x32_bf16 v[98:101], v[180:183], v[204:207], v[98:101]
	v_mfma_f32_16x16x32_bf16 v[82:85], v[180:183], v[212:215], v[82:85]
	v_mfma_f32_16x16x32_bf16 v[86:89], v[162:165], v[212:215], v[86:89]
	v_mfma_f32_16x16x32_bf16 v[134:137], v[176:179], v[192:195], v[134:137]
	v_mfma_f32_16x16x32_bf16 v[130:133], v[184:187], v[192:195], v[130:133]
	v_mfma_f32_16x16x32_bf16 v[114:117], v[184:187], v[200:203], v[114:117]
	v_mfma_f32_16x16x32_bf16 v[118:121], v[176:179], v[200:203], v[118:121]
	v_mfma_f32_16x16x32_bf16 v[102:105], v[176:179], v[208:211], v[102:105]
	v_mfma_f32_16x16x32_bf16 v[98:101], v[184:187], v[208:211], v[98:101]
	v_mfma_f32_16x16x32_bf16 v[82:85], v[184:187], v[216:219], v[82:85]
	v_mfma_f32_16x16x32_bf16 v[86:89], v[176:179], v[216:219], v[86:89]
	s_setprio 0
	s_barrier
	s_add_i32 s45, s37, s27
	v_lshl_add_u64 v[172:173], s[20:21], 0, v[150:151]
	s_mov_b32 m0, s45
	ds_read_b128 v[188:191], v170 offset:16384
	ds_read_b128 v[192:195], v170 offset:17408
	ds_read_b128 v[196:199], v170 offset:18432
	ds_read_b128 v[200:203], v170 offset:19456
	ds_read_b128 v[204:207], v170 offset:20480
	ds_read_b128 v[208:211], v170 offset:21504
	ds_read_b128 v[212:215], v170 offset:22528
	ds_read_b128 v[216:219], v170 offset:23552
	global_load_lds_dwordx4 v[172:173], off
	s_add_i32 m0, s45, 0x2000
	s_add_u32 s46, s20, 0x80000
	v_lshl_add_u64 v[220:221], s[20:21], 0, v[146:147]
	s_addc_u32 s47, s21, 0
	s_add_i32 s45, s38, s27
	global_load_lds_dwordx4 v[220:221], off
	v_lshl_add_u64 v[222:223], s[46:47], 0, v[150:151]
	s_mov_b32 m0, s45
	v_lshl_add_u64 v[224:225], s[22:23], 0, v[148:149]
	global_load_lds_dwordx4 v[222:223], off
	v_lshl_add_u64 v[222:223], s[46:47], 0, v[146:147]
	s_add_i32 m0, s45, 0x2000
	s_nop 0
	global_load_lds_dwordx4 v[222:223], off
	v_lshl_add_u64 v[222:223], s[22:23], 0, v[152:153]
	s_mov_b32 m0, s19
	s_nop 0
	global_load_lds_dwordx4 v[222:223], off
	s_mov_b32 m0, s28
	s_nop 0
	global_load_lds_dwordx4 v[224:225], off
	s_waitcnt vmcnt(8)
	s_waitcnt lgkmcnt(0)
	s_barrier
	s_setprio 1
	s_waitcnt lgkmcnt(0)
	v_mfma_f32_16x16x32_bf16 v[70:73], v[58:61], v[188:191], v[70:73]
	v_mfma_f32_16x16x32_bf16 v[66:69], v[74:77], v[188:191], v[66:69]
	v_mfma_f32_16x16x32_bf16 v[42:45], v[74:77], v[196:199], v[42:45]
	v_mfma_f32_16x16x32_bf16 v[46:49], v[58:61], v[196:199], v[46:49]
	v_mfma_f32_16x16x32_bf16 v[30:33], v[58:61], v[204:207], v[30:33]
	v_mfma_f32_16x16x32_bf16 v[26:29], v[74:77], v[204:207], v[26:29]
	v_mfma_f32_16x16x32_bf16 v[10:13], v[74:77], v[212:215], v[10:13]
	v_mfma_f32_16x16x32_bf16 v[14:17], v[58:61], v[212:215], v[14:17]
	v_mfma_f32_16x16x32_bf16 v[70:73], v[62:65], v[192:195], v[70:73]
	v_mfma_f32_16x16x32_bf16 v[66:69], v[78:81], v[192:195], v[66:69]
	v_mfma_f32_16x16x32_bf16 v[42:45], v[78:81], v[200:203], v[42:45]
	v_mfma_f32_16x16x32_bf16 v[46:49], v[62:65], v[200:203], v[46:49]
	v_mfma_f32_16x16x32_bf16 v[30:33], v[62:65], v[208:211], v[30:33]
	v_mfma_f32_16x16x32_bf16 v[26:29], v[78:81], v[208:211], v[26:29]
	v_mfma_f32_16x16x32_bf16 v[10:13], v[78:81], v[216:219], v[10:13]
	v_mfma_f32_16x16x32_bf16 v[14:17], v[62:65], v[216:219], v[14:17]
	s_setprio 0
	s_setprio 1
	v_mfma_f32_16x16x32_bf16 v[54:57], v[162:165], v[188:191], v[54:57]
	v_mfma_f32_16x16x32_bf16 v[50:53], v[180:183], v[188:191], v[50:53]
	v_mfma_f32_16x16x32_bf16 v[34:37], v[180:183], v[196:199], v[34:37]
	v_mfma_f32_16x16x32_bf16 v[38:41], v[162:165], v[196:199], v[38:41]
	v_mfma_f32_16x16x32_bf16 v[22:25], v[162:165], v[204:207], v[22:25]
	v_mfma_f32_16x16x32_bf16 v[18:21], v[180:183], v[204:207], v[18:21]
	v_mfma_f32_16x16x32_bf16 v[2:5], v[180:183], v[212:215], v[2:5]
	v_mfma_f32_16x16x32_bf16 v[6:9], v[162:165], v[212:215], v[6:9]
	v_mfma_f32_16x16x32_bf16 v[54:57], v[176:179], v[192:195], v[54:57]
	v_mfma_f32_16x16x32_bf16 v[50:53], v[184:187], v[192:195], v[50:53]
	v_mfma_f32_16x16x32_bf16 v[34:37], v[184:187], v[200:203], v[34:37]
	v_mfma_f32_16x16x32_bf16 v[38:41], v[176:179], v[200:203], v[38:41]
	v_mfma_f32_16x16x32_bf16 v[22:25], v[176:179], v[208:211], v[22:25]
	v_mfma_f32_16x16x32_bf16 v[18:21], v[184:187], v[208:211], v[18:21]
	v_mfma_f32_16x16x32_bf16 v[2:5], v[184:187], v[216:219], v[2:5]
	v_mfma_f32_16x16x32_bf16 v[6:9], v[176:179], v[216:219], v[6:9]
	s_setprio 0
	s_barrier
	s_add_i32 s45, 0, 0x18000
	s_add_i32 s46, 0, 0x1c000
	v_add_u32_e32 v78, s45, v166
	v_add_u32_e32 v171, s46, v166
	ds_read_b128 v[58:61], v78
	ds_read_b128 v[62:65], v78 offset:1024
	ds_read_b128 v[74:77], v78 offset:2048
	ds_read_b128 v[78:81], v78 offset:3072
	ds_read_b128 v[162:165], v171
	ds_read_b128 v[176:179], v171 offset:1024
	ds_read_b128 v[180:183], v171 offset:2048
	ds_read_b128 v[184:187], v171 offset:3072
	s_add_u32 s22, s22, 0x80000
	s_addc_u32 s23, s23, 0
	s_mov_b32 m0, s29
	v_lshl_add_u64 v[226:227], s[22:23], 0, v[152:153]
	ds_read_b128 v[188:191], v170 offset:32768
	ds_read_b128 v[192:195], v170 offset:33792
	ds_read_b128 v[196:199], v170 offset:34816
	ds_read_b128 v[200:203], v170 offset:35840
	ds_read_b128 v[204:207], v170 offset:36864
	ds_read_b128 v[208:211], v170 offset:37888
	ds_read_b128 v[212:215], v170 offset:38912
	ds_read_b128 v[216:219], v170 offset:39936
	global_load_lds_dwordx4 v[226:227], off
	v_lshl_add_u64 v[226:227], s[22:23], 0, v[148:149]
	s_mov_b32 m0, s30
	s_nop 0
	global_load_lds_dwordx4 v[226:227], off
	s_waitcnt vmcnt(8)
	s_waitcnt lgkmcnt(0)
	s_barrier
	s_setprio 1
	s_waitcnt lgkmcnt(0)
	v_mfma_f32_16x16x32_bf16 v[142:145], v[58:61], v[188:191], v[142:145]
	v_mfma_f32_16x16x32_bf16 v[138:141], v[74:77], v[188:191], v[138:141]
	v_mfma_f32_16x16x32_bf16 v[122:125], v[74:77], v[196:199], v[122:125]
	v_mfma_f32_16x16x32_bf16 v[126:129], v[58:61], v[196:199], v[126:129]
	v_mfma_f32_16x16x32_bf16 v[110:113], v[58:61], v[204:207], v[110:113]
	v_mfma_f32_16x16x32_bf16 v[106:109], v[74:77], v[204:207], v[106:109]
	v_mfma_f32_16x16x32_bf16 v[90:93], v[74:77], v[212:215], v[90:93]
	v_mfma_f32_16x16x32_bf16 v[94:97], v[58:61], v[212:215], v[94:97]
	v_mfma_f32_16x16x32_bf16 v[142:145], v[62:65], v[192:195], v[142:145]
	v_mfma_f32_16x16x32_bf16 v[138:141], v[78:81], v[192:195], v[138:141]
	v_mfma_f32_16x16x32_bf16 v[122:125], v[78:81], v[200:203], v[122:125]
	v_mfma_f32_16x16x32_bf16 v[126:129], v[62:65], v[200:203], v[126:129]
	v_mfma_f32_16x16x32_bf16 v[110:113], v[62:65], v[208:211], v[110:113]
	v_mfma_f32_16x16x32_bf16 v[106:109], v[78:81], v[208:211], v[106:109]
	v_mfma_f32_16x16x32_bf16 v[90:93], v[78:81], v[216:219], v[90:93]
	v_mfma_f32_16x16x32_bf16 v[94:97], v[62:65], v[216:219], v[94:97]
	s_setprio 0
	s_setprio 1
	v_mfma_f32_16x16x32_bf16 v[134:137], v[162:165], v[188:191], v[134:137]
	v_mfma_f32_16x16x32_bf16 v[130:133], v[180:183], v[188:191], v[130:133]
	v_mfma_f32_16x16x32_bf16 v[114:117], v[180:183], v[196:199], v[114:117]
	v_mfma_f32_16x16x32_bf16 v[118:121], v[162:165], v[196:199], v[118:121]
	v_mfma_f32_16x16x32_bf16 v[102:105], v[162:165], v[204:207], v[102:105]
	v_mfma_f32_16x16x32_bf16 v[98:101], v[180:183], v[204:207], v[98:101]
	v_mfma_f32_16x16x32_bf16 v[82:85], v[180:183], v[212:215], v[82:85]
	v_mfma_f32_16x16x32_bf16 v[86:89], v[162:165], v[212:215], v[86:89]
	v_mfma_f32_16x16x32_bf16 v[134:137], v[176:179], v[192:195], v[134:137]
	v_mfma_f32_16x16x32_bf16 v[130:133], v[184:187], v[192:195], v[130:133]
	v_mfma_f32_16x16x32_bf16 v[114:117], v[184:187], v[200:203], v[114:117]
	v_mfma_f32_16x16x32_bf16 v[118:121], v[176:179], v[200:203], v[118:121]
	v_mfma_f32_16x16x32_bf16 v[102:105], v[176:179], v[208:211], v[102:105]
	v_mfma_f32_16x16x32_bf16 v[98:101], v[184:187], v[208:211], v[98:101]
	v_mfma_f32_16x16x32_bf16 v[82:85], v[184:187], v[216:219], v[82:85]
	v_mfma_f32_16x16x32_bf16 v[86:89], v[176:179], v[216:219], v[86:89]
	s_setprio 0
	s_barrier
	s_add_i32 s22, s45, s27
	v_lshl_add_u64 v[172:173], v[172:173], 0, s[14:15]
	s_mov_b32 m0, s22
	ds_read_b128 v[188:191], v170 offset:49152
	ds_read_b128 v[192:195], v170 offset:50176
	ds_read_b128 v[196:199], v170 offset:51200
	ds_read_b128 v[200:203], v170 offset:52224
	ds_read_b128 v[204:207], v170 offset:53248
	ds_read_b128 v[208:211], v170 offset:54272
	ds_read_b128 v[212:215], v170 offset:55296
	ds_read_b128 v[216:219], v170 offset:56320
	global_load_lds_dwordx4 v[172:173], off
	s_add_i32 m0, s22, 0x2000
	s_add_u32 s20, s20, 0x80080
	v_lshl_add_u64 v[172:173], v[220:221], 0, s[14:15]
	s_addc_u32 s21, s21, 0
	s_add_i32 s22, s46, s27
	global_load_lds_dwordx4 v[172:173], off
	v_lshl_add_u64 v[172:173], s[20:21], 0, v[150:151]
	s_mov_b32 m0, s22
	s_nop 0
	global_load_lds_dwordx4 v[172:173], off
	v_lshl_add_u64 v[172:173], s[20:21], 0, v[146:147]
	s_add_i32 m0, s22, 0x2000
	s_nop 0
	global_load_lds_dwordx4 v[172:173], off
	v_lshl_add_u64 v[172:173], v[222:223], 0, s[14:15]
	s_mov_b32 m0, s33
	s_nop 0
	global_load_lds_dwordx4 v[172:173], off
	v_lshl_add_u64 v[172:173], v[224:225], 0, s[14:15]
	s_mov_b32 m0, s34
	s_nop 0
	global_load_lds_dwordx4 v[172:173], off
	s_waitcnt vmcnt(8)
	s_waitcnt lgkmcnt(0)
	s_barrier
	s_setprio 1
	s_waitcnt lgkmcnt(0)
	v_mfma_f32_16x16x32_bf16 v[70:73], v[58:61], v[188:191], v[70:73]
	v_mfma_f32_16x16x32_bf16 v[66:69], v[74:77], v[188:191], v[66:69]
	v_mfma_f32_16x16x32_bf16 v[42:45], v[74:77], v[196:199], v[42:45]
	v_mfma_f32_16x16x32_bf16 v[46:49], v[58:61], v[196:199], v[46:49]
	v_mfma_f32_16x16x32_bf16 v[30:33], v[58:61], v[204:207], v[30:33]
	v_mfma_f32_16x16x32_bf16 v[26:29], v[74:77], v[204:207], v[26:29]
	v_mfma_f32_16x16x32_bf16 v[10:13], v[74:77], v[212:215], v[10:13]
	v_mfma_f32_16x16x32_bf16 v[14:17], v[58:61], v[212:215], v[14:17]
	v_mfma_f32_16x16x32_bf16 v[70:73], v[62:65], v[192:195], v[70:73]
	v_mfma_f32_16x16x32_bf16 v[66:69], v[78:81], v[192:195], v[66:69]
	v_mfma_f32_16x16x32_bf16 v[42:45], v[78:81], v[200:203], v[42:45]
	v_mfma_f32_16x16x32_bf16 v[46:49], v[62:65], v[200:203], v[46:49]
	v_mfma_f32_16x16x32_bf16 v[30:33], v[62:65], v[208:211], v[30:33]
	v_mfma_f32_16x16x32_bf16 v[26:29], v[78:81], v[208:211], v[26:29]
	v_mfma_f32_16x16x32_bf16 v[10:13], v[78:81], v[216:219], v[10:13]
	v_mfma_f32_16x16x32_bf16 v[14:17], v[62:65], v[216:219], v[14:17]
	s_setprio 0
	s_setprio 1
	v_mfma_f32_16x16x32_bf16 v[54:57], v[162:165], v[188:191], v[54:57]
	v_mfma_f32_16x16x32_bf16 v[50:53], v[180:183], v[188:191], v[50:53]
	v_mfma_f32_16x16x32_bf16 v[34:37], v[180:183], v[196:199], v[34:37]
	v_mfma_f32_16x16x32_bf16 v[38:41], v[162:165], v[196:199], v[38:41]
	v_mfma_f32_16x16x32_bf16 v[22:25], v[162:165], v[204:207], v[22:25]
	v_mfma_f32_16x16x32_bf16 v[18:21], v[180:183], v[204:207], v[18:21]
	v_mfma_f32_16x16x32_bf16 v[2:5], v[180:183], v[212:215], v[2:5]
	v_mfma_f32_16x16x32_bf16 v[6:9], v[162:165], v[212:215], v[6:9]
	v_mfma_f32_16x16x32_bf16 v[54:57], v[176:179], v[192:195], v[54:57]
	v_mfma_f32_16x16x32_bf16 v[50:53], v[184:187], v[192:195], v[50:53]
	v_mfma_f32_16x16x32_bf16 v[34:37], v[184:187], v[200:203], v[34:37]
	v_mfma_f32_16x16x32_bf16 v[38:41], v[176:179], v[200:203], v[38:41]
	v_mfma_f32_16x16x32_bf16 v[22:25], v[176:179], v[208:211], v[22:25]
	v_mfma_f32_16x16x32_bf16 v[18:21], v[184:187], v[208:211], v[18:21]
	v_mfma_f32_16x16x32_bf16 v[2:5], v[184:187], v[216:219], v[2:5]
	v_mfma_f32_16x16x32_bf16 v[6:9], v[176:179], v[216:219], v[6:9]
	s_setprio 0
	s_barrier
	s_add_i32 s44, s44, 2
	s_add_u32 s0, s0, 0x100
	s_addc_u32 s1, s1, 0
	s_add_u32 s42, s42, 0x100
	s_addc_u32 s43, s43, 0
	s_cmp_gt_u32 s44, 29
	s_cbranch_scc0 .LBB0_508
	v_lshl_or_b32 v58, s39, 8, v167
	v_readlane_b32 s60, v243, 17
	v_ashrrev_i32_e32 v59, 31, v58
	v_readlane_b32 s70, v243, 27
	v_readlane_b32 s71, v243, 28
	v_lshl_add_u32 v164, s18, 8, v1
	v_ashrrev_i32_e32 v165, 31, v164
	v_lshl_add_u64 v[62:63], v[58:59], 2, s[70:71]
	global_load_dwordx4 v[78:81], v[62:63], off
	global_load_dwordx4 v[74:77], v[62:63], off offset:16
	v_lshlrev_b64 v[60:61], 12, v[164:165]
	v_lshlrev_b64 v[162:163], 1, v[58:59]
	v_lshl_add_u64 v[58:59], s[6:7], 0, v[60:61]
	v_lshl_add_u64 v[172:173], v[58:59], 0, v[162:163]
	global_load_dwordx4 v[176:179], v[172:173], off
	global_load_dwordx4 v[58:61], v[62:63], off offset:528
	s_nop 0
	global_load_dwordx4 v[62:65], v[62:63], off offset:512
	s_and_b64 vcc, exec, vcc
	s_mov_b32 s18, s16
	s_mov_b32 s39, s2
	v_readlane_b32 s61, v243, 18
	v_readlane_b32 s62, v243, 19
	v_readlane_b32 s63, v243, 20
	v_readlane_b32 s64, v243, 21
	v_readlane_b32 s65, v243, 22
	v_readlane_b32 s66, v243, 23
	v_readlane_b32 s67, v243, 24
	v_readlane_b32 s68, v243, 25
	v_readlane_b32 s69, v243, 26
	v_readlane_b32 s72, v243, 29
	v_readlane_b32 s73, v243, 30
	v_readlane_b32 s74, v243, 31
	v_readlane_b32 s75, v243, 32
	s_waitcnt vmcnt(0)
	v_pk_add_f32 v[144:145], v[144:145], v[80:81]
	v_pk_add_f32 v[142:143], v[142:143], v[78:79]
	v_pk_add_f32 v[140:141], v[140:141], v[76:77]
	v_pk_add_f32 v[138:139], v[138:139], v[74:75]
	v_mul_f32_e32 v142, 0xbfb8aa3b, v142
	v_mul_f32_e32 v138, 0xbfb8aa3b, v138
	v_mul_f32_e32 v143, 0xbfb8aa3b, v143
	v_mul_f32_e32 v139, 0xbfb8aa3b, v139
	v_mul_f32_e32 v144, 0xbfb8aa3b, v144
	v_mul_f32_e32 v140, 0xbfb8aa3b, v140
	v_mul_f32_e32 v145, 0xbfb8aa3b, v145
	v_mul_f32_e32 v141, 0xbfb8aa3b, v141
	v_exp_f32_e32 v142, v142
	v_exp_f32_e32 v138, v138
	v_exp_f32_e32 v143, v143
	v_exp_f32_e32 v139, v139
	v_exp_f32_e32 v144, v144
	v_exp_f32_e32 v140, v140
	v_exp_f32_e32 v145, v145
	v_exp_f32_e32 v141, v141
	v_add_f32_e32 v142, 1.0, v142
	v_add_f32_e32 v138, 1.0, v138
	v_add_f32_e32 v143, 1.0, v143
	v_add_f32_e32 v139, 1.0, v139
	v_add_f32_e32 v144, 1.0, v144
	v_add_f32_e32 v140, 1.0, v140
	v_add_f32_e32 v145, 1.0, v145
	v_add_f32_e32 v141, 1.0, v141
	v_rcp_f32_e32 v142, v142
	v_rcp_f32_e32 v138, v138
	v_rcp_f32_e32 v143, v143
	v_rcp_f32_e32 v139, v139
	v_rcp_f32_e32 v144, v144
	v_rcp_f32_e32 v140, v140
	v_rcp_f32_e32 v145, v145
	v_rcp_f32_e32 v141, v141
	v_lshlrev_b32_e32 v171, 16, v176
	v_and_b32_e32 v175, 0xffff0000, v176
	v_lshlrev_b32_e32 v176, 16, v177
	v_and_b32_e32 v177, 0xffff0000, v177
	v_lshlrev_b32_e32 v180, 16, v178
	v_and_b32_e32 v178, 0xffff0000, v178
	v_lshlrev_b32_e32 v181, 16, v179
	v_and_b32_e32 v179, 0xffff0000, v179
	v_mul_f32_e32 v142, v142, v171
	v_mul_f32_e32 v171, v138, v180
	v_mul_f32_e32 v138, v143, v175
	v_mul_f32_e32 v143, v139, v178
	v_mul_f32_e32 v139, v144, v176
	v_mul_f32_e32 v144, v140, v181
	v_mul_f32_e32 v140, v145, v177
	v_mul_f32_e32 v141, v141, v179
	v_cvt_pk_bf16_f32 v138, v142, v138
	v_cvt_pk_bf16_f32 v139, v139, v140
	v_cvt_pk_bf16_f32 v140, v171, v143
	v_cvt_pk_bf16_f32 v141, v144, v141
	global_load_dwordx4 v[142:145], v[172:173], off offset:256
	v_pk_add_f32 v[136:137], v[136:137], v[64:65]
	v_pk_add_f32 v[134:135], v[134:135], v[62:63]
	v_pk_add_f32 v[132:133], v[132:133], v[60:61]
	v_pk_add_f32 v[130:131], v[130:131], v[58:59]
	v_mul_f32_e32 v134, 0xbfb8aa3b, v134
	v_mul_f32_e32 v130, 0xbfb8aa3b, v130
	v_mul_f32_e32 v135, 0xbfb8aa3b, v135
	v_mul_f32_e32 v131, 0xbfb8aa3b, v131
	v_mul_f32_e32 v136, 0xbfb8aa3b, v136
	v_mul_f32_e32 v132, 0xbfb8aa3b, v132
	v_mul_f32_e32 v137, 0xbfb8aa3b, v137
	v_mul_f32_e32 v133, 0xbfb8aa3b, v133
	v_exp_f32_e32 v134, v134
	v_exp_f32_e32 v130, v130
	v_exp_f32_e32 v135, v135
	v_exp_f32_e32 v131, v131
	v_exp_f32_e32 v136, v136
	v_exp_f32_e32 v132, v132
	v_exp_f32_e32 v137, v137
	v_exp_f32_e32 v133, v133
	v_add_f32_e32 v134, 1.0, v134
	v_add_f32_e32 v130, 1.0, v130
	v_add_f32_e32 v135, 1.0, v135
	v_add_f32_e32 v131, 1.0, v131
	v_add_f32_e32 v136, 1.0, v136
	v_add_f32_e32 v132, 1.0, v132
	v_add_f32_e32 v137, 1.0, v137
	v_add_f32_e32 v133, 1.0, v133
	v_or_b32_e32 v172, 16, v164
	v_lshlrev_b64 v[176:177], 13, v[164:165]
	v_rcp_f32_e32 v134, v134
	v_rcp_f32_e32 v130, v130
	v_rcp_f32_e32 v135, v135
	v_rcp_f32_e32 v131, v131
	v_rcp_f32_e32 v136, v136
	v_rcp_f32_e32 v132, v132
	v_rcp_f32_e32 v137, v137
	v_rcp_f32_e32 v133, v133
	v_ashrrev_i32_e32 v173, 31, v172
	v_lshl_add_u64 v[176:177], s[12:13], 0, v[176:177]
	v_lshlrev_b64 v[178:179], 12, v[172:173]
	v_lshl_add_u64 v[176:177], v[176:177], 0, v[162:163]
	v_lshl_add_u64 v[178:179], s[6:7], 0, v[178:179]
	global_store_dwordx4 v[176:177], v[138:141], off
	v_lshl_add_u64 v[178:179], v[178:179], 0, v[162:163]
	v_pk_add_f32 v[128:129], v[128:129], v[80:81]
	v_pk_add_f32 v[126:127], v[126:127], v[78:79]
	v_pk_add_f32 v[124:125], v[124:125], v[76:77]
	v_pk_add_f32 v[122:123], v[122:123], v[74:75]
	v_mul_f32_e32 v126, 0xbfb8aa3b, v126
	v_mul_f32_e32 v122, 0xbfb8aa3b, v122
	v_mul_f32_e32 v127, 0xbfb8aa3b, v127
	v_mul_f32_e32 v123, 0xbfb8aa3b, v123
	v_mul_f32_e32 v128, 0xbfb8aa3b, v128
	v_mul_f32_e32 v124, 0xbfb8aa3b, v124
	v_mul_f32_e32 v129, 0xbfb8aa3b, v129
	v_mul_f32_e32 v125, 0xbfb8aa3b, v125
	v_exp_f32_e32 v126, v126
	v_exp_f32_e32 v122, v122
	v_exp_f32_e32 v127, v127
	v_exp_f32_e32 v123, v123
	v_exp_f32_e32 v128, v128
	v_exp_f32_e32 v124, v124
	v_exp_f32_e32 v129, v129
	v_exp_f32_e32 v125, v125
	v_add_f32_e32 v126, 1.0, v126
	v_add_f32_e32 v122, 1.0, v122
	v_add_f32_e32 v127, 1.0, v127
	v_add_f32_e32 v123, 1.0, v123
	v_add_f32_e32 v128, 1.0, v128
	v_add_f32_e32 v124, 1.0, v124
	v_add_f32_e32 v129, 1.0, v129
	v_add_f32_e32 v125, 1.0, v125
	v_rcp_f32_e32 v126, v126
	v_rcp_f32_e32 v122, v122
	v_rcp_f32_e32 v127, v127
	v_rcp_f32_e32 v123, v123
	v_rcp_f32_e32 v128, v128
	v_rcp_f32_e32 v124, v124
	s_waitcnt vmcnt(1)
	v_lshlrev_b32_e32 v138, 16, v142
	v_and_b32_e32 v139, 0xffff0000, v142
	v_lshlrev_b32_e32 v140, 16, v143
	v_and_b32_e32 v141, 0xffff0000, v143
	v_lshlrev_b32_e32 v142, 16, v144
	v_and_b32_e32 v143, 0xffff0000, v144
	v_lshlrev_b32_e32 v144, 16, v145
	v_and_b32_e32 v145, 0xffff0000, v145
	v_mul_f32_e32 v134, v134, v138
	v_mul_f32_e32 v138, v130, v142
	v_mul_f32_e32 v130, v135, v139
	v_mul_f32_e32 v135, v131, v143
	v_mul_f32_e32 v131, v136, v140
	v_mul_f32_e32 v136, v132, v144
	v_mul_f32_e32 v132, v137, v141
	v_mul_f32_e32 v133, v133, v145
	v_cvt_pk_bf16_f32 v130, v134, v130
	v_cvt_pk_bf16_f32 v131, v131, v132
	v_cvt_pk_bf16_f32 v132, v138, v135
	v_cvt_pk_bf16_f32 v133, v136, v133
	global_load_dwordx4 v[134:137], v[178:179], off
	v_rcp_f32_e32 v129, v129
	v_rcp_f32_e32 v125, v125
	global_store_dwordx4 v[176:177], v[130:133], off offset:256
	v_pk_add_f32 v[120:121], v[120:121], v[64:65]
	v_pk_add_f32 v[118:119], v[118:119], v[62:63]
	v_pk_add_f32 v[116:117], v[116:117], v[60:61]
	v_pk_add_f32 v[114:115], v[114:115], v[58:59]
	v_mul_f32_e32 v118, 0xbfb8aa3b, v118
	v_mul_f32_e32 v114, 0xbfb8aa3b, v114
	v_mul_f32_e32 v119, 0xbfb8aa3b, v119
	v_mul_f32_e32 v115, 0xbfb8aa3b, v115
	v_mul_f32_e32 v120, 0xbfb8aa3b, v120
	v_mul_f32_e32 v116, 0xbfb8aa3b, v116
	v_mul_f32_e32 v121, 0xbfb8aa3b, v121
	v_mul_f32_e32 v117, 0xbfb8aa3b, v117
	v_exp_f32_e32 v118, v118
	v_exp_f32_e32 v114, v114
	v_exp_f32_e32 v119, v119
	v_exp_f32_e32 v115, v115
	v_exp_f32_e32 v120, v120
	v_exp_f32_e32 v116, v116
	v_exp_f32_e32 v121, v121
	v_exp_f32_e32 v117, v117
	v_add_f32_e32 v118, 1.0, v118
	v_add_f32_e32 v114, 1.0, v114
	v_add_f32_e32 v119, 1.0, v119
	v_add_f32_e32 v115, 1.0, v115
	v_add_f32_e32 v120, 1.0, v120
	v_add_f32_e32 v116, 1.0, v116
	v_add_f32_e32 v121, 1.0, v121
	v_add_f32_e32 v117, 1.0, v117
	v_rcp_f32_e32 v118, v118
	v_rcp_f32_e32 v114, v114
	v_rcp_f32_e32 v119, v119
	v_rcp_f32_e32 v115, v115
	v_rcp_f32_e32 v120, v120
	v_rcp_f32_e32 v116, v116
	v_rcp_f32_e32 v121, v121
	v_rcp_f32_e32 v117, v117
	v_pk_add_f32 v[112:113], v[112:113], v[80:81]
	v_pk_add_f32 v[110:111], v[110:111], v[78:79]
	v_pk_add_f32 v[108:109], v[108:109], v[76:77]
	v_pk_add_f32 v[106:107], v[106:107], v[74:75]
	v_mul_f32_e32 v110, 0xbfb8aa3b, v110
	v_mul_f32_e32 v106, 0xbfb8aa3b, v106
	v_mul_f32_e32 v111, 0xbfb8aa3b, v111
	v_mul_f32_e32 v107, 0xbfb8aa3b, v107
	v_mul_f32_e32 v112, 0xbfb8aa3b, v112
	v_mul_f32_e32 v108, 0xbfb8aa3b, v108
	v_mul_f32_e32 v113, 0xbfb8aa3b, v113
	v_mul_f32_e32 v109, 0xbfb8aa3b, v109
	v_exp_f32_e32 v110, v110
	v_exp_f32_e32 v106, v106
	v_exp_f32_e32 v111, v111
	v_exp_f32_e32 v107, v107
	v_exp_f32_e32 v112, v112
	v_exp_f32_e32 v108, v108
	v_exp_f32_e32 v113, v113
	v_exp_f32_e32 v109, v109
	v_add_f32_e32 v110, 1.0, v110
	v_add_f32_e32 v106, 1.0, v106
	v_add_f32_e32 v111, 1.0, v111
	v_add_f32_e32 v107, 1.0, v107
	v_add_f32_e32 v112, 1.0, v112
	v_add_f32_e32 v108, 1.0, v108
	v_add_f32_e32 v113, 1.0, v113
	v_add_f32_e32 v109, 1.0, v109
	v_rcp_f32_e32 v110, v110
	v_rcp_f32_e32 v106, v106
	v_rcp_f32_e32 v111, v111
	v_rcp_f32_e32 v107, v107
	v_rcp_f32_e32 v112, v112
	v_rcp_f32_e32 v108, v108
	v_rcp_f32_e32 v113, v113
	v_rcp_f32_e32 v109, v109
	v_pk_add_f32 v[104:105], v[104:105], v[64:65]
	v_pk_add_f32 v[102:103], v[102:103], v[62:63]
	v_pk_add_f32 v[100:101], v[100:101], v[60:61]
	v_pk_add_f32 v[98:99], v[98:99], v[58:59]
	s_waitcnt vmcnt(1)
	v_lshlrev_b32_e32 v130, 16, v134
	v_and_b32_e32 v131, 0xffff0000, v134
	v_lshlrev_b32_e32 v132, 16, v135
	v_and_b32_e32 v133, 0xffff0000, v135
	v_lshlrev_b32_e32 v134, 16, v136
	v_and_b32_e32 v135, 0xffff0000, v136
	v_lshlrev_b32_e32 v136, 16, v137
	v_and_b32_e32 v137, 0xffff0000, v137
	v_mul_f32_e32 v126, v126, v130
	v_mul_f32_e32 v130, v122, v134
	v_mul_f32_e32 v122, v127, v131
	v_mul_f32_e32 v127, v123, v135
	v_mul_f32_e32 v123, v128, v132
	v_mul_f32_e32 v128, v124, v136
	v_mul_f32_e32 v124, v129, v133
	v_mul_f32_e32 v125, v125, v137
	v_cvt_pk_bf16_f32 v122, v126, v122
	v_cvt_pk_bf16_f32 v123, v123, v124
	v_cvt_pk_bf16_f32 v124, v130, v127
	v_cvt_pk_bf16_f32 v125, v128, v125
	global_load_dwordx4 v[126:129], v[178:179], off offset:256
	v_or_b32_e32 v130, 32, v164
	v_lshlrev_b64 v[132:133], 13, v[172:173]
	v_ashrrev_i32_e32 v131, 31, v130
	v_lshl_add_u64 v[132:133], s[12:13], 0, v[132:133]
	v_lshlrev_b64 v[134:135], 12, v[130:131]
	v_lshl_add_u64 v[132:133], v[132:133], 0, v[162:163]
	v_lshl_add_u64 v[134:135], s[6:7], 0, v[134:135]
	global_store_dwordx4 v[132:133], v[122:125], off
	v_lshl_add_u64 v[134:135], v[134:135], 0, v[162:163]
	v_mul_f32_e32 v102, 0xbfb8aa3b, v102
	v_mul_f32_e32 v98, 0xbfb8aa3b, v98
	v_mul_f32_e32 v103, 0xbfb8aa3b, v103
	v_mul_f32_e32 v99, 0xbfb8aa3b, v99
	v_mul_f32_e32 v104, 0xbfb8aa3b, v104
	v_mul_f32_e32 v100, 0xbfb8aa3b, v100
	v_mul_f32_e32 v105, 0xbfb8aa3b, v105
	v_mul_f32_e32 v101, 0xbfb8aa3b, v101
	v_exp_f32_e32 v102, v102
	v_exp_f32_e32 v98, v98
	v_exp_f32_e32 v103, v103
	v_exp_f32_e32 v99, v99
	v_exp_f32_e32 v104, v104
	v_exp_f32_e32 v100, v100
	v_exp_f32_e32 v105, v105
	v_exp_f32_e32 v101, v101
	v_add_f32_e32 v102, 1.0, v102
	v_add_f32_e32 v98, 1.0, v98
	v_add_f32_e32 v103, 1.0, v103
	v_add_f32_e32 v99, 1.0, v99
	v_add_f32_e32 v104, 1.0, v104
	v_add_f32_e32 v100, 1.0, v100
	v_add_f32_e32 v105, 1.0, v105
	v_add_f32_e32 v101, 1.0, v101
	v_rcp_f32_e32 v102, v102
	v_rcp_f32_e32 v98, v98
	v_rcp_f32_e32 v103, v103
	v_rcp_f32_e32 v99, v99
	v_rcp_f32_e32 v104, v104
	v_rcp_f32_e32 v100, v100
	v_rcp_f32_e32 v105, v105
	v_rcp_f32_e32 v101, v101
	v_pk_add_f32 v[96:97], v[96:97], v[80:81]
	v_pk_add_f32 v[94:95], v[94:95], v[78:79]
	v_pk_add_f32 v[92:93], v[92:93], v[76:77]
	v_pk_add_f32 v[90:91], v[90:91], v[74:75]
	v_mul_f32_e32 v94, 0xbfb8aa3b, v94
	v_mul_f32_e32 v90, 0xbfb8aa3b, v90
	v_mul_f32_e32 v95, 0xbfb8aa3b, v95
	v_mul_f32_e32 v91, 0xbfb8aa3b, v91
	v_mul_f32_e32 v96, 0xbfb8aa3b, v96
	v_mul_f32_e32 v92, 0xbfb8aa3b, v92
	v_mul_f32_e32 v97, 0xbfb8aa3b, v97
	v_mul_f32_e32 v93, 0xbfb8aa3b, v93
	v_exp_f32_e32 v94, v94
	v_exp_f32_e32 v90, v90
	v_exp_f32_e32 v95, v95
	v_exp_f32_e32 v91, v91
	v_exp_f32_e32 v96, v96
	v_exp_f32_e32 v92, v92
	v_exp_f32_e32 v97, v97
	v_exp_f32_e32 v93, v93
	v_add_f32_e32 v94, 1.0, v94
	v_add_f32_e32 v90, 1.0, v90
	v_add_f32_e32 v95, 1.0, v95
	v_add_f32_e32 v91, 1.0, v91
	v_add_f32_e32 v96, 1.0, v96
	v_add_f32_e32 v92, 1.0, v92
	v_add_f32_e32 v97, 1.0, v97
	v_add_f32_e32 v93, 1.0, v93
	v_rcp_f32_e32 v94, v94
	v_rcp_f32_e32 v90, v90
	v_rcp_f32_e32 v95, v95
	v_rcp_f32_e32 v91, v91
	v_rcp_f32_e32 v96, v96
	v_rcp_f32_e32 v92, v92
	v_rcp_f32_e32 v97, v97
	v_rcp_f32_e32 v93, v93
	v_pk_add_f32 v[88:89], v[88:89], v[64:65]
	v_pk_add_f32 v[86:87], v[86:87], v[62:63]
	s_waitcnt vmcnt(1)
	v_lshlrev_b32_e32 v122, 16, v126
	v_and_b32_e32 v123, 0xffff0000, v126
	v_lshlrev_b32_e32 v124, 16, v127
	v_and_b32_e32 v125, 0xffff0000, v127
	v_lshlrev_b32_e32 v126, 16, v128
	v_and_b32_e32 v127, 0xffff0000, v128
	v_lshlrev_b32_e32 v128, 16, v129
	v_and_b32_e32 v129, 0xffff0000, v129
	v_mul_f32_e32 v118, v118, v122
	v_mul_f32_e32 v122, v114, v126
	v_mul_f32_e32 v114, v119, v123
	v_mul_f32_e32 v119, v115, v127
	v_mul_f32_e32 v115, v120, v124
	v_mul_f32_e32 v120, v116, v128
	v_mul_f32_e32 v116, v121, v125
	v_mul_f32_e32 v117, v117, v129
	v_cvt_pk_bf16_f32 v114, v118, v114
	v_cvt_pk_bf16_f32 v115, v115, v116
	v_cvt_pk_bf16_f32 v116, v122, v119
	v_cvt_pk_bf16_f32 v117, v120, v117
	global_load_dwordx4 v[118:121], v[134:135], off
	v_pk_add_f32 v[84:85], v[84:85], v[60:61]
	global_store_dwordx4 v[132:133], v[114:117], off offset:256
	v_pk_add_f32 v[82:83], v[82:83], v[58:59]
	v_mul_f32_e32 v86, 0xbfb8aa3b, v86
	v_mul_f32_e32 v82, 0xbfb8aa3b, v82
	v_mul_f32_e32 v87, 0xbfb8aa3b, v87
	v_mul_f32_e32 v83, 0xbfb8aa3b, v83
	v_mul_f32_e32 v88, 0xbfb8aa3b, v88
	v_mul_f32_e32 v84, 0xbfb8aa3b, v84
	v_mul_f32_e32 v89, 0xbfb8aa3b, v89
	v_mul_f32_e32 v85, 0xbfb8aa3b, v85
	v_exp_f32_e32 v86, v86
	v_exp_f32_e32 v82, v82
	v_exp_f32_e32 v87, v87
	v_exp_f32_e32 v83, v83
	v_exp_f32_e32 v88, v88
	v_exp_f32_e32 v84, v84
	v_exp_f32_e32 v89, v89
	v_exp_f32_e32 v85, v85
	v_add_f32_e32 v86, 1.0, v86
	v_add_f32_e32 v82, 1.0, v82
	v_add_f32_e32 v87, 1.0, v87
	v_add_f32_e32 v83, 1.0, v83
	v_add_f32_e32 v88, 1.0, v88
	v_add_f32_e32 v84, 1.0, v84
	v_add_f32_e32 v89, 1.0, v89
	v_add_f32_e32 v85, 1.0, v85
	v_rcp_f32_e32 v86, v86
	v_rcp_f32_e32 v82, v82
	v_rcp_f32_e32 v87, v87
	v_rcp_f32_e32 v83, v83
	v_rcp_f32_e32 v88, v88
	v_rcp_f32_e32 v84, v84
	v_rcp_f32_e32 v89, v89
	v_rcp_f32_e32 v85, v85
	v_pk_add_f32 v[72:73], v[72:73], v[80:81]
	v_pk_add_f32 v[70:71], v[70:71], v[78:79]
	v_pk_add_f32 v[68:69], v[68:69], v[76:77]
	v_pk_add_f32 v[66:67], v[66:67], v[74:75]
	v_mul_f32_e32 v70, 0xbfb8aa3b, v70
	v_mul_f32_e32 v66, 0xbfb8aa3b, v66
	v_mul_f32_e32 v71, 0xbfb8aa3b, v71
	v_mul_f32_e32 v67, 0xbfb8aa3b, v67
	v_mul_f32_e32 v72, 0xbfb8aa3b, v72
	v_mul_f32_e32 v68, 0xbfb8aa3b, v68
	v_mul_f32_e32 v73, 0xbfb8aa3b, v73
	v_mul_f32_e32 v69, 0xbfb8aa3b, v69
	v_exp_f32_e32 v70, v70
	v_exp_f32_e32 v66, v66
	v_exp_f32_e32 v71, v71
	v_exp_f32_e32 v67, v67
	v_exp_f32_e32 v72, v72
	v_exp_f32_e32 v68, v68
	v_exp_f32_e32 v73, v73
	v_exp_f32_e32 v69, v69
	v_add_f32_e32 v70, 1.0, v70
	v_add_f32_e32 v66, 1.0, v66
	v_add_f32_e32 v71, 1.0, v71
	v_add_f32_e32 v67, 1.0, v67
	v_add_f32_e32 v72, 1.0, v72
	v_add_f32_e32 v68, 1.0, v68
	v_add_f32_e32 v73, 1.0, v73
	v_add_f32_e32 v69, 1.0, v69
	v_rcp_f32_e32 v70, v70
	v_rcp_f32_e32 v66, v66
	v_rcp_f32_e32 v71, v71
	v_rcp_f32_e32 v67, v67
	v_rcp_f32_e32 v72, v72
	v_rcp_f32_e32 v68, v68
	v_rcp_f32_e32 v73, v73
	v_rcp_f32_e32 v69, v69
	v_pk_add_f32 v[56:57], v[56:57], v[64:65]
	v_pk_add_f32 v[54:55], v[54:55], v[62:63]
	v_pk_add_f32 v[52:53], v[52:53], v[60:61]
	v_pk_add_f32 v[50:51], v[50:51], v[58:59]
	v_mul_f32_e32 v54, 0xbfb8aa3b, v54
	v_mul_f32_e32 v50, 0xbfb8aa3b, v50
	v_mul_f32_e32 v55, 0xbfb8aa3b, v55
	v_mul_f32_e32 v51, 0xbfb8aa3b, v51
	s_waitcnt vmcnt(1)
	v_lshlrev_b32_e32 v114, 16, v118
	v_and_b32_e32 v115, 0xffff0000, v118
	v_lshlrev_b32_e32 v116, 16, v119
	v_and_b32_e32 v117, 0xffff0000, v119
	v_lshlrev_b32_e32 v118, 16, v120
	v_and_b32_e32 v119, 0xffff0000, v120
	v_lshlrev_b32_e32 v120, 16, v121
	v_and_b32_e32 v121, 0xffff0000, v121
	v_mul_f32_e32 v110, v110, v114
	v_mul_f32_e32 v114, v106, v118
	v_mul_f32_e32 v106, v111, v115
	v_mul_f32_e32 v111, v107, v119
	v_mul_f32_e32 v107, v112, v116
	v_mul_f32_e32 v112, v108, v120
	v_mul_f32_e32 v108, v113, v117
	v_mul_f32_e32 v109, v109, v121
	v_cvt_pk_bf16_f32 v106, v110, v106
	v_cvt_pk_bf16_f32 v107, v107, v108
	v_cvt_pk_bf16_f32 v108, v114, v111
	v_cvt_pk_bf16_f32 v109, v112, v109
	global_load_dwordx4 v[110:113], v[134:135], off offset:256
	v_or_b32_e32 v114, 48, v164
	v_lshlrev_b64 v[116:117], 13, v[130:131]
	v_ashrrev_i32_e32 v115, 31, v114
	v_lshl_add_u64 v[116:117], s[12:13], 0, v[116:117]
	v_lshlrev_b64 v[118:119], 12, v[114:115]
	v_lshl_add_u64 v[116:117], v[116:117], 0, v[162:163]
	v_lshl_add_u64 v[118:119], s[6:7], 0, v[118:119]
	global_store_dwordx4 v[116:117], v[106:109], off
	v_lshl_add_u64 v[118:119], v[118:119], 0, v[162:163]
	v_mul_f32_e32 v56, 0xbfb8aa3b, v56
	v_mul_f32_e32 v52, 0xbfb8aa3b, v52
	v_mul_f32_e32 v57, 0xbfb8aa3b, v57
	v_mul_f32_e32 v53, 0xbfb8aa3b, v53
	v_exp_f32_e32 v54, v54
	v_exp_f32_e32 v50, v50
	v_exp_f32_e32 v55, v55
	v_exp_f32_e32 v51, v51
	v_exp_f32_e32 v56, v56
	v_exp_f32_e32 v52, v52
	v_exp_f32_e32 v57, v57
	v_exp_f32_e32 v53, v53
	v_add_f32_e32 v54, 1.0, v54
	v_add_f32_e32 v50, 1.0, v50
	v_add_f32_e32 v55, 1.0, v55
	v_add_f32_e32 v51, 1.0, v51
	v_add_f32_e32 v56, 1.0, v56
	v_add_f32_e32 v52, 1.0, v52
	v_add_f32_e32 v57, 1.0, v57
	v_add_f32_e32 v53, 1.0, v53
	v_rcp_f32_e32 v54, v54
	v_rcp_f32_e32 v50, v50
	v_rcp_f32_e32 v55, v55
	v_rcp_f32_e32 v51, v51
	v_rcp_f32_e32 v56, v56
	v_rcp_f32_e32 v52, v52
	v_rcp_f32_e32 v57, v57
	v_rcp_f32_e32 v53, v53
	v_pk_add_f32 v[48:49], v[48:49], v[80:81]
	v_pk_add_f32 v[46:47], v[46:47], v[78:79]
	v_pk_add_f32 v[44:45], v[44:45], v[76:77]
	v_pk_add_f32 v[42:43], v[42:43], v[74:75]
	v_mul_f32_e32 v46, 0xbfb8aa3b, v46
	v_mul_f32_e32 v42, 0xbfb8aa3b, v42
	v_mul_f32_e32 v47, 0xbfb8aa3b, v47
	v_mul_f32_e32 v43, 0xbfb8aa3b, v43
	v_mul_f32_e32 v48, 0xbfb8aa3b, v48
	v_mul_f32_e32 v44, 0xbfb8aa3b, v44
	v_mul_f32_e32 v49, 0xbfb8aa3b, v49
	v_mul_f32_e32 v45, 0xbfb8aa3b, v45
	v_exp_f32_e32 v46, v46
	v_exp_f32_e32 v42, v42
	v_exp_f32_e32 v47, v47
	v_exp_f32_e32 v43, v43
	v_exp_f32_e32 v48, v48
	v_exp_f32_e32 v44, v44
	v_exp_f32_e32 v49, v49
	v_exp_f32_e32 v45, v45
	v_add_f32_e32 v46, 1.0, v46
	v_add_f32_e32 v42, 1.0, v42
	v_add_f32_e32 v47, 1.0, v47
	v_add_f32_e32 v43, 1.0, v43
	v_add_f32_e32 v48, 1.0, v48
	v_add_f32_e32 v44, 1.0, v44
	v_add_f32_e32 v49, 1.0, v49
	v_add_f32_e32 v45, 1.0, v45
	v_rcp_f32_e32 v46, v46
	v_rcp_f32_e32 v42, v42
	v_rcp_f32_e32 v47, v47
	v_rcp_f32_e32 v43, v43
	v_rcp_f32_e32 v48, v48
	v_rcp_f32_e32 v44, v44
	v_rcp_f32_e32 v49, v49
	v_rcp_f32_e32 v45, v45
	v_pk_add_f32 v[40:41], v[40:41], v[64:65]
	v_pk_add_f32 v[38:39], v[38:39], v[62:63]
	v_pk_add_f32 v[36:37], v[36:37], v[60:61]
	v_pk_add_f32 v[34:35], v[34:35], v[58:59]
	v_mul_f32_e32 v38, 0xbfb8aa3b, v38
	v_mul_f32_e32 v34, 0xbfb8aa3b, v34
	s_waitcnt vmcnt(1)
	v_lshlrev_b32_e32 v106, 16, v110
	v_and_b32_e32 v107, 0xffff0000, v110
	v_lshlrev_b32_e32 v108, 16, v111
	v_and_b32_e32 v109, 0xffff0000, v111
	v_lshlrev_b32_e32 v110, 16, v112
	v_and_b32_e32 v111, 0xffff0000, v112
	v_lshlrev_b32_e32 v112, 16, v113
	v_and_b32_e32 v113, 0xffff0000, v113
	v_mul_f32_e32 v102, v102, v106
	v_mul_f32_e32 v106, v98, v110
	v_mul_f32_e32 v98, v103, v107
	v_mul_f32_e32 v103, v99, v111
	v_mul_f32_e32 v99, v104, v108
	v_mul_f32_e32 v104, v100, v112
	v_mul_f32_e32 v100, v105, v109
	v_mul_f32_e32 v101, v101, v113
	v_cvt_pk_bf16_f32 v98, v102, v98
	v_cvt_pk_bf16_f32 v99, v99, v100
	v_cvt_pk_bf16_f32 v100, v106, v103
	v_cvt_pk_bf16_f32 v101, v104, v101
	global_load_dwordx4 v[102:105], v[118:119], off
	v_mul_f32_e32 v39, 0xbfb8aa3b, v39
	global_store_dwordx4 v[116:117], v[98:101], off offset:256
	v_mul_f32_e32 v35, 0xbfb8aa3b, v35
	v_mul_f32_e32 v40, 0xbfb8aa3b, v40
	v_mul_f32_e32 v36, 0xbfb8aa3b, v36
	v_mul_f32_e32 v41, 0xbfb8aa3b, v41
	v_mul_f32_e32 v37, 0xbfb8aa3b, v37
	v_exp_f32_e32 v38, v38
	v_exp_f32_e32 v34, v34
	v_exp_f32_e32 v39, v39
	v_exp_f32_e32 v35, v35
	v_exp_f32_e32 v40, v40
	v_exp_f32_e32 v36, v36
	v_exp_f32_e32 v41, v41
	v_exp_f32_e32 v37, v37
	v_add_f32_e32 v38, 1.0, v38
	v_add_f32_e32 v34, 1.0, v34
	v_add_f32_e32 v39, 1.0, v39
	v_add_f32_e32 v35, 1.0, v35
	v_add_f32_e32 v40, 1.0, v40
	v_add_f32_e32 v36, 1.0, v36
	v_add_f32_e32 v41, 1.0, v41
	v_add_f32_e32 v37, 1.0, v37
	v_rcp_f32_e32 v38, v38
	v_rcp_f32_e32 v34, v34
	v_rcp_f32_e32 v39, v39
	v_rcp_f32_e32 v35, v35
	v_rcp_f32_e32 v40, v40
	v_rcp_f32_e32 v36, v36
	v_rcp_f32_e32 v41, v41
	v_rcp_f32_e32 v37, v37
	v_pk_add_f32 v[32:33], v[32:33], v[80:81]
	v_pk_add_f32 v[30:31], v[30:31], v[78:79]
	v_pk_add_f32 v[28:29], v[28:29], v[76:77]
	v_pk_add_f32 v[26:27], v[26:27], v[74:75]
	v_mul_f32_e32 v30, 0xbfb8aa3b, v30
	v_mul_f32_e32 v26, 0xbfb8aa3b, v26
	v_mul_f32_e32 v31, 0xbfb8aa3b, v31
	v_mul_f32_e32 v27, 0xbfb8aa3b, v27
	v_mul_f32_e32 v32, 0xbfb8aa3b, v32
	v_mul_f32_e32 v28, 0xbfb8aa3b, v28
	v_mul_f32_e32 v33, 0xbfb8aa3b, v33
	v_mul_f32_e32 v29, 0xbfb8aa3b, v29
	v_exp_f32_e32 v30, v30
	v_exp_f32_e32 v26, v26
	v_exp_f32_e32 v31, v31
	v_exp_f32_e32 v27, v27
	v_exp_f32_e32 v32, v32
	v_exp_f32_e32 v28, v28
	v_exp_f32_e32 v33, v33
	v_exp_f32_e32 v29, v29
	v_add_f32_e32 v30, 1.0, v30
	v_add_f32_e32 v26, 1.0, v26
	v_add_f32_e32 v31, 1.0, v31
	v_add_f32_e32 v27, 1.0, v27
	v_add_f32_e32 v32, 1.0, v32
	v_add_f32_e32 v28, 1.0, v28
	v_add_f32_e32 v33, 1.0, v33
	v_add_f32_e32 v29, 1.0, v29
	v_rcp_f32_e32 v30, v30
	v_rcp_f32_e32 v26, v26
	v_rcp_f32_e32 v31, v31
	v_rcp_f32_e32 v27, v27
	v_rcp_f32_e32 v32, v32
	v_rcp_f32_e32 v28, v28
	v_rcp_f32_e32 v33, v33
	v_rcp_f32_e32 v29, v29
	v_pk_add_f32 v[24:25], v[24:25], v[64:65]
	v_pk_add_f32 v[22:23], v[22:23], v[62:63]
	v_pk_add_f32 v[20:21], v[20:21], v[60:61]
	v_pk_add_f32 v[18:19], v[18:19], v[58:59]
	v_mul_f32_e32 v22, 0xbfb8aa3b, v22
	v_mul_f32_e32 v18, 0xbfb8aa3b, v18
	v_mul_f32_e32 v23, 0xbfb8aa3b, v23
	v_mul_f32_e32 v19, 0xbfb8aa3b, v19
	v_mul_f32_e32 v24, 0xbfb8aa3b, v24
	v_mul_f32_e32 v20, 0xbfb8aa3b, v20
	v_mul_f32_e32 v25, 0xbfb8aa3b, v25
	v_mul_f32_e32 v21, 0xbfb8aa3b, v21
	s_waitcnt vmcnt(1)
	v_lshlrev_b32_e32 v98, 16, v102
	v_and_b32_e32 v99, 0xffff0000, v102
	v_lshlrev_b32_e32 v100, 16, v103
	v_and_b32_e32 v101, 0xffff0000, v103
	v_lshlrev_b32_e32 v102, 16, v104
	v_and_b32_e32 v103, 0xffff0000, v104
	v_lshlrev_b32_e32 v104, 16, v105
	v_and_b32_e32 v105, 0xffff0000, v105
	v_mul_f32_e32 v94, v94, v98
	v_mul_f32_e32 v98, v90, v102
	v_mul_f32_e32 v90, v95, v99
	v_mul_f32_e32 v95, v91, v103
	v_mul_f32_e32 v91, v96, v100
	v_mul_f32_e32 v96, v92, v104
	v_mul_f32_e32 v92, v97, v101
	v_mul_f32_e32 v93, v93, v105
	v_cvt_pk_bf16_f32 v90, v94, v90
	v_cvt_pk_bf16_f32 v91, v91, v92
	v_cvt_pk_bf16_f32 v92, v98, v95
	v_cvt_pk_bf16_f32 v93, v96, v93
	global_load_dwordx4 v[94:97], v[118:119], off offset:256
	v_add_u32_e32 v98, 0x80, v164
	v_lshlrev_b64 v[100:101], 13, v[114:115]
	v_ashrrev_i32_e32 v99, 31, v98
	v_lshl_add_u64 v[100:101], s[12:13], 0, v[100:101]
	v_lshlrev_b64 v[102:103], 12, v[98:99]
	v_lshl_add_u64 v[100:101], v[100:101], 0, v[162:163]
	v_lshl_add_u64 v[102:103], s[6:7], 0, v[102:103]
	global_store_dwordx4 v[100:101], v[90:93], off
	v_lshl_add_u64 v[102:103], v[102:103], 0, v[162:163]
	v_exp_f32_e32 v22, v22
	v_exp_f32_e32 v18, v18
	v_exp_f32_e32 v23, v23
	v_exp_f32_e32 v19, v19
	v_exp_f32_e32 v24, v24
	v_exp_f32_e32 v20, v20
	v_exp_f32_e32 v25, v25
	v_exp_f32_e32 v21, v21
	v_add_f32_e32 v22, 1.0, v22
	v_add_f32_e32 v18, 1.0, v18
	v_add_f32_e32 v23, 1.0, v23
	v_add_f32_e32 v19, 1.0, v19
	v_add_f32_e32 v24, 1.0, v24
	v_add_f32_e32 v20, 1.0, v20
	v_add_f32_e32 v25, 1.0, v25
	v_add_f32_e32 v21, 1.0, v21
	v_rcp_f32_e32 v22, v22
	v_rcp_f32_e32 v18, v18
	v_rcp_f32_e32 v23, v23
	v_rcp_f32_e32 v19, v19
	v_rcp_f32_e32 v24, v24
	v_rcp_f32_e32 v20, v20
	v_rcp_f32_e32 v25, v25
	v_rcp_f32_e32 v21, v21
	v_pk_add_f32 v[16:17], v[16:17], v[80:81]
	v_pk_add_f32 v[14:15], v[14:15], v[78:79]
	v_pk_add_f32 v[12:13], v[12:13], v[76:77]
	v_pk_add_f32 v[10:11], v[10:11], v[74:75]
	v_mul_f32_e32 v14, 0xbfb8aa3b, v14
	v_mul_f32_e32 v10, 0xbfb8aa3b, v10
	v_mul_f32_e32 v15, 0xbfb8aa3b, v15
	v_mul_f32_e32 v11, 0xbfb8aa3b, v11
	v_mul_f32_e32 v16, 0xbfb8aa3b, v16
	v_mul_f32_e32 v12, 0xbfb8aa3b, v12
	v_mul_f32_e32 v17, 0xbfb8aa3b, v17
	v_mul_f32_e32 v13, 0xbfb8aa3b, v13
	v_exp_f32_e32 v14, v14
	v_exp_f32_e32 v10, v10
	v_exp_f32_e32 v15, v15
	v_exp_f32_e32 v11, v11
	v_exp_f32_e32 v16, v16
	v_exp_f32_e32 v12, v12
	v_exp_f32_e32 v17, v17
	v_exp_f32_e32 v13, v13
	v_add_f32_e32 v14, 1.0, v14
	v_add_f32_e32 v10, 1.0, v10
	v_add_f32_e32 v15, 1.0, v15
	v_add_f32_e32 v11, 1.0, v11
	v_add_f32_e32 v16, 1.0, v16
	v_add_f32_e32 v12, 1.0, v12
	v_add_f32_e32 v17, 1.0, v17
	v_add_f32_e32 v13, 1.0, v13
	v_rcp_f32_e32 v14, v14
	v_rcp_f32_e32 v10, v10
	v_rcp_f32_e32 v15, v15
	v_rcp_f32_e32 v11, v11
	v_rcp_f32_e32 v16, v16
	v_rcp_f32_e32 v12, v12
	v_rcp_f32_e32 v17, v17
	v_rcp_f32_e32 v13, v13
	v_pk_add_f32 v[8:9], v[8:9], v[64:65]
	v_pk_add_f32 v[6:7], v[6:7], v[62:63]
	v_pk_add_f32 v[4:5], v[4:5], v[60:61]
	v_pk_add_f32 v[2:3], v[2:3], v[58:59]
	v_mul_f32_e32 v6, 0xbfb8aa3b, v6
	v_mul_f32_e32 v2, 0xbfb8aa3b, v2
	v_mul_f32_e32 v7, 0xbfb8aa3b, v7
	v_mul_f32_e32 v3, 0xbfb8aa3b, v3
	v_mul_f32_e32 v8, 0xbfb8aa3b, v8
	v_mul_f32_e32 v4, 0xbfb8aa3b, v4
	s_waitcnt vmcnt(1)
	v_lshlrev_b32_e32 v90, 16, v94
	v_and_b32_e32 v91, 0xffff0000, v94
	v_lshlrev_b32_e32 v92, 16, v95
	v_and_b32_e32 v93, 0xffff0000, v95
	v_lshlrev_b32_e32 v94, 16, v96
	v_and_b32_e32 v95, 0xffff0000, v96
	v_lshlrev_b32_e32 v96, 16, v97
	v_and_b32_e32 v97, 0xffff0000, v97
	v_mul_f32_e32 v86, v86, v90
	v_mul_f32_e32 v90, v82, v94
	v_mul_f32_e32 v82, v87, v91
	v_mul_f32_e32 v87, v83, v95
	v_mul_f32_e32 v83, v88, v92
	v_mul_f32_e32 v88, v84, v96
	v_mul_f32_e32 v84, v89, v93
	v_mul_f32_e32 v85, v85, v97
	v_cvt_pk_bf16_f32 v82, v86, v82
	v_cvt_pk_bf16_f32 v83, v83, v84
	v_cvt_pk_bf16_f32 v84, v90, v87
	v_cvt_pk_bf16_f32 v85, v88, v85
	global_load_dwordx4 v[86:89], v[102:103], off
	v_mul_f32_e32 v9, 0xbfb8aa3b, v9
	global_store_dwordx4 v[100:101], v[82:85], off offset:256
	v_mul_f32_e32 v5, 0xbfb8aa3b, v5
	v_exp_f32_e32 v6, v6
	v_exp_f32_e32 v2, v2
	v_exp_f32_e32 v7, v7
	v_exp_f32_e32 v3, v3
	v_exp_f32_e32 v8, v8
	v_exp_f32_e32 v4, v4
	v_exp_f32_e32 v9, v9
	v_exp_f32_e32 v5, v5
	v_add_f32_e32 v6, 1.0, v6
	v_add_f32_e32 v2, 1.0, v2
	v_add_f32_e32 v7, 1.0, v7
	v_add_f32_e32 v3, 1.0, v3
	v_add_f32_e32 v8, 1.0, v8
	v_add_f32_e32 v4, 1.0, v4
	v_add_f32_e32 v9, 1.0, v9
	v_add_f32_e32 v5, 1.0, v5
	v_rcp_f32_e32 v6, v6
	v_rcp_f32_e32 v2, v2
	v_rcp_f32_e32 v7, v7
	v_rcp_f32_e32 v3, v3
	v_rcp_f32_e32 v8, v8
	v_rcp_f32_e32 v4, v4
	v_rcp_f32_e32 v9, v9
	v_rcp_f32_e32 v5, v5
	s_waitcnt vmcnt(1)
	v_lshlrev_b32_e32 v82, 16, v86
	v_and_b32_e32 v83, 0xffff0000, v86
	v_lshlrev_b32_e32 v84, 16, v87
	v_and_b32_e32 v85, 0xffff0000, v87
	v_lshlrev_b32_e32 v86, 16, v88
	v_and_b32_e32 v87, 0xffff0000, v88
	v_lshlrev_b32_e32 v88, 16, v89
	v_and_b32_e32 v89, 0xffff0000, v89
	v_mul_f32_e32 v70, v70, v82
	v_mul_f32_e32 v82, v66, v86
	v_mul_f32_e32 v66, v71, v83
	v_mul_f32_e32 v71, v67, v87
	v_mul_f32_e32 v67, v72, v84
	v_mul_f32_e32 v72, v68, v88
	v_mul_f32_e32 v68, v73, v85
	v_mul_f32_e32 v69, v69, v89
	v_cvt_pk_bf16_f32 v66, v70, v66
	v_cvt_pk_bf16_f32 v67, v67, v68
	v_cvt_pk_bf16_f32 v68, v82, v71
	v_cvt_pk_bf16_f32 v69, v72, v69
	global_load_dwordx4 v[70:73], v[102:103], off offset:256
	v_add_u32_e32 v82, 0x90, v164
	v_lshlrev_b64 v[84:85], 13, v[98:99]
	v_ashrrev_i32_e32 v83, 31, v82
	v_lshl_add_u64 v[84:85], s[12:13], 0, v[84:85]
	v_lshlrev_b64 v[86:87], 12, v[82:83]
	v_lshl_add_u64 v[84:85], v[84:85], 0, v[162:163]
	v_lshl_add_u64 v[86:87], s[6:7], 0, v[86:87]
	global_store_dwordx4 v[84:85], v[66:69], off
	v_lshl_add_u64 v[86:87], v[86:87], 0, v[162:163]
	s_waitcnt vmcnt(1)
	v_lshlrev_b32_e32 v66, 16, v70
	v_and_b32_e32 v67, 0xffff0000, v70
	v_lshlrev_b32_e32 v68, 16, v71
	v_and_b32_e32 v69, 0xffff0000, v71
	v_lshlrev_b32_e32 v70, 16, v72
	v_and_b32_e32 v71, 0xffff0000, v72
	v_lshlrev_b32_e32 v72, 16, v73
	v_and_b32_e32 v73, 0xffff0000, v73
	v_mul_f32_e32 v54, v54, v66
	v_mul_f32_e32 v66, v50, v70
	v_mul_f32_e32 v50, v55, v67
	v_mul_f32_e32 v55, v51, v71
	v_mul_f32_e32 v51, v56, v68
	v_mul_f32_e32 v56, v52, v72
	v_mul_f32_e32 v52, v57, v69
	v_mul_f32_e32 v53, v53, v73
	v_cvt_pk_bf16_f32 v50, v54, v50
	v_cvt_pk_bf16_f32 v51, v51, v52
	v_cvt_pk_bf16_f32 v52, v66, v55
	v_cvt_pk_bf16_f32 v53, v56, v53
	global_load_dwordx4 v[54:57], v[86:87], off
	s_nop 0
	global_store_dwordx4 v[84:85], v[50:53], off offset:256
	s_waitcnt vmcnt(1)
	s_nop 0
	v_lshlrev_b32_e32 v50, 16, v54
	v_and_b32_e32 v51, 0xffff0000, v54
	v_lshlrev_b32_e32 v52, 16, v55
	v_and_b32_e32 v53, 0xffff0000, v55
	v_lshlrev_b32_e32 v54, 16, v56
	v_and_b32_e32 v55, 0xffff0000, v56
	v_lshlrev_b32_e32 v56, 16, v57
	v_and_b32_e32 v57, 0xffff0000, v57
	v_mul_f32_e32 v46, v46, v50
	v_mul_f32_e32 v50, v42, v54
	v_mul_f32_e32 v42, v47, v51
	v_mul_f32_e32 v47, v43, v55
	v_mul_f32_e32 v43, v48, v52
	v_mul_f32_e32 v48, v44, v56
	v_mul_f32_e32 v44, v49, v53
	v_mul_f32_e32 v45, v45, v57
	v_cvt_pk_bf16_f32 v42, v46, v42
	v_cvt_pk_bf16_f32 v43, v43, v44
	v_cvt_pk_bf16_f32 v44, v50, v47
	v_cvt_pk_bf16_f32 v45, v48, v45
	global_load_dwordx4 v[46:49], v[86:87], off offset:256
	v_add_u32_e32 v50, 0xa0, v164
	v_lshlrev_b64 v[52:53], 13, v[82:83]
	v_ashrrev_i32_e32 v51, 31, v50
	v_lshl_add_u64 v[52:53], s[12:13], 0, v[52:53]
	v_lshlrev_b64 v[54:55], 12, v[50:51]
	v_lshl_add_u64 v[52:53], v[52:53], 0, v[162:163]
	v_lshl_add_u64 v[54:55], s[6:7], 0, v[54:55]
	global_store_dwordx4 v[52:53], v[42:45], off
	v_lshl_add_u64 v[54:55], v[54:55], 0, v[162:163]
	s_waitcnt vmcnt(1)
	v_lshlrev_b32_e32 v42, 16, v46
	v_and_b32_e32 v43, 0xffff0000, v46
	v_lshlrev_b32_e32 v44, 16, v47
	v_and_b32_e32 v45, 0xffff0000, v47
	v_lshlrev_b32_e32 v46, 16, v48
	v_and_b32_e32 v47, 0xffff0000, v48
	v_lshlrev_b32_e32 v48, 16, v49
	v_and_b32_e32 v49, 0xffff0000, v49
	v_mul_f32_e32 v38, v38, v42
	v_mul_f32_e32 v42, v34, v46
	v_mul_f32_e32 v34, v39, v43
	v_mul_f32_e32 v39, v35, v47
	v_mul_f32_e32 v35, v40, v44
	v_mul_f32_e32 v40, v36, v48
	v_mul_f32_e32 v36, v41, v45
	v_mul_f32_e32 v37, v37, v49
	v_cvt_pk_bf16_f32 v34, v38, v34
	v_cvt_pk_bf16_f32 v35, v35, v36
	v_cvt_pk_bf16_f32 v36, v42, v39
	v_cvt_pk_bf16_f32 v37, v40, v37
	global_load_dwordx4 v[38:41], v[54:55], off
	s_nop 0
	global_store_dwordx4 v[52:53], v[34:37], off offset:256
	s_waitcnt vmcnt(1)
	s_nop 0
	v_lshlrev_b32_e32 v34, 16, v38
	v_and_b32_e32 v35, 0xffff0000, v38
	v_lshlrev_b32_e32 v36, 16, v39
	v_and_b32_e32 v37, 0xffff0000, v39
	v_lshlrev_b32_e32 v38, 16, v40
	v_and_b32_e32 v39, 0xffff0000, v40
	v_lshlrev_b32_e32 v40, 16, v41
	v_and_b32_e32 v41, 0xffff0000, v41
	v_mul_f32_e32 v30, v30, v34
	v_mul_f32_e32 v34, v26, v38
	v_mul_f32_e32 v26, v31, v35
	v_mul_f32_e32 v31, v27, v39
	v_mul_f32_e32 v27, v32, v36
	v_mul_f32_e32 v32, v28, v40
	v_mul_f32_e32 v28, v33, v37
	v_mul_f32_e32 v29, v29, v41
	v_cvt_pk_bf16_f32 v26, v30, v26
	v_cvt_pk_bf16_f32 v27, v27, v28
	v_cvt_pk_bf16_f32 v28, v34, v31
	v_cvt_pk_bf16_f32 v29, v32, v29
	global_load_dwordx4 v[30:33], v[54:55], off offset:256
	v_add_u32_e32 v34, 0xb0, v164
	v_lshlrev_b64 v[36:37], 13, v[50:51]
	v_ashrrev_i32_e32 v35, 31, v34
	v_lshl_add_u64 v[36:37], s[12:13], 0, v[36:37]
	v_lshlrev_b64 v[38:39], 12, v[34:35]
	v_lshl_add_u64 v[36:37], v[36:37], 0, v[162:163]
	v_lshl_add_u64 v[38:39], s[6:7], 0, v[38:39]
	global_store_dwordx4 v[36:37], v[26:29], off
	v_lshl_add_u64 v[38:39], v[38:39], 0, v[162:163]
	s_waitcnt vmcnt(1)
	v_lshlrev_b32_e32 v26, 16, v30
	v_and_b32_e32 v27, 0xffff0000, v30
	v_lshlrev_b32_e32 v28, 16, v31
	v_and_b32_e32 v29, 0xffff0000, v31
	v_lshlrev_b32_e32 v30, 16, v32
	v_and_b32_e32 v31, 0xffff0000, v32
	v_lshlrev_b32_e32 v32, 16, v33
	v_and_b32_e32 v33, 0xffff0000, v33
	v_mul_f32_e32 v22, v22, v26
	v_mul_f32_e32 v26, v18, v30
	v_mul_f32_e32 v18, v23, v27
	v_mul_f32_e32 v23, v19, v31
	v_mul_f32_e32 v19, v24, v28
	v_mul_f32_e32 v24, v20, v32
	v_mul_f32_e32 v20, v25, v29
	v_mul_f32_e32 v21, v21, v33
	v_cvt_pk_bf16_f32 v18, v22, v18
	v_cvt_pk_bf16_f32 v19, v19, v20
	v_cvt_pk_bf16_f32 v20, v26, v23
	v_cvt_pk_bf16_f32 v21, v24, v21
	global_load_dwordx4 v[22:25], v[38:39], off
	s_nop 0
	global_store_dwordx4 v[36:37], v[18:21], off offset:256
	s_waitcnt vmcnt(1)
	s_nop 0
	v_lshlrev_b32_e32 v18, 16, v22
	v_and_b32_e32 v19, 0xffff0000, v22
	v_lshlrev_b32_e32 v20, 16, v23
	v_and_b32_e32 v21, 0xffff0000, v23
	v_lshlrev_b32_e32 v22, 16, v24
	v_and_b32_e32 v23, 0xffff0000, v24
	v_lshlrev_b32_e32 v24, 16, v25
	v_and_b32_e32 v25, 0xffff0000, v25
	v_mul_f32_e32 v14, v14, v18
	v_mul_f32_e32 v18, v10, v22
	v_mul_f32_e32 v10, v15, v19
	v_mul_f32_e32 v15, v11, v23
	v_mul_f32_e32 v11, v16, v20
	v_mul_f32_e32 v16, v12, v24
	v_mul_f32_e32 v12, v17, v21
	v_mul_f32_e32 v13, v13, v25
	v_cvt_pk_bf16_f32 v10, v14, v10
	v_cvt_pk_bf16_f32 v11, v11, v12
	v_cvt_pk_bf16_f32 v12, v18, v15
	v_cvt_pk_bf16_f32 v13, v16, v13
	global_load_dwordx4 v[14:17], v[38:39], off offset:256
	v_lshlrev_b64 v[18:19], 13, v[34:35]
	v_lshl_add_u64 v[18:19], s[12:13], 0, v[18:19]
	v_lshl_add_u64 v[18:19], v[18:19], 0, v[162:163]
	global_store_dwordx4 v[18:19], v[10:13], off
	s_waitcnt vmcnt(1)
	s_nop 0
	v_lshlrev_b32_e32 v10, 16, v14
	v_and_b32_e32 v11, 0xffff0000, v14
	v_lshlrev_b32_e32 v12, 16, v15
	v_and_b32_e32 v13, 0xffff0000, v15
	v_lshlrev_b32_e32 v14, 16, v16
	v_and_b32_e32 v15, 0xffff0000, v16
	v_lshlrev_b32_e32 v16, 16, v17
	v_and_b32_e32 v17, 0xffff0000, v17
	v_mul_f32_e32 v6, v6, v10
	v_mul_f32_e32 v10, v2, v14
	v_mul_f32_e32 v2, v7, v11
	v_mul_f32_e32 v7, v3, v15
	v_mul_f32_e32 v3, v8, v12
	v_mul_f32_e32 v8, v4, v16
	v_mul_f32_e32 v4, v9, v13
	v_mul_f32_e32 v5, v5, v17
	v_cvt_pk_bf16_f32 v2, v6, v2
	v_cvt_pk_bf16_f32 v3, v3, v4
	v_cvt_pk_bf16_f32 v4, v10, v7
	v_cvt_pk_bf16_f32 v5, v8, v5
	global_store_dwordx4 v[18:19], v[2:5], off offset:256
	s_cbranch_vccz .LBB0_507
	s_waitcnt vmcnt(0)
	s_cmpk_gt_u32 s24, 0xff
	s_cbranch_scc1 .LBB0_512
	s_barrier

.LBB0_595:
	s_add_i32 s62, s30, 2
	s_add_u32 s31, s28, 0xfff00080
	s_addc_u32 s34, s29, -1
	s_add_i32 s63, 0, 0x10000
	v_add_u32_e32 v148, s63, v1
	ds_read_b128 v[152:155], v148
	ds_read_b128 v[156:159], v148 offset:1024
	ds_read_b128 v[160:163], v148 offset:2048
	ds_read_b128 v[164:167], v148 offset:3072
	ds_read_b128 v[168:171], v150
	ds_read_b128 v[176:179], v150 offset:1024
	ds_read_b128 v[180:183], v150 offset:2048
	ds_read_b128 v[184:187], v150 offset:3072
	s_cmp_eq_u32 s25, s30
	s_cselect_b32 s30, s26, s60
	s_cselect_b32 s35, s15, s34
	s_cselect_b32 s34, s14, s31
	s_cselect_b32 s31, s27, s61
	v_lshl_add_u64 v[148:149], s[28:29], 0, v[142:143]
	s_add_i32 m0, s17, 0xc000
	ds_read_b128 v[188:191], v151
	ds_read_b128 v[192:195], v151 offset:1024
	ds_read_b128 v[196:199], v151 offset:2048
	ds_read_b128 v[200:203], v151 offset:3072
	ds_read_b128 v[204:207], v151 offset:4096
	ds_read_b128 v[208:211], v151 offset:5120
	ds_read_b128 v[212:215], v151 offset:6144
	ds_read_b128 v[216:219], v151 offset:7168
	global_load_lds_dwordx4 v[148:149], off
	v_lshl_add_u64 v[148:149], s[28:29], 0, v[144:145]
	s_add_i32 m0, s17, 0xe000
	s_nop 0
	global_load_lds_dwordx4 v[148:149], off
	s_waitcnt vmcnt(8)
	s_waitcnt lgkmcnt(0)
	s_barrier
	s_setprio 1
	s_waitcnt lgkmcnt(0)
	v_mfma_f32_16x16x32_bf16 v[126:129], v[152:155], v[188:191], v[126:129]
	v_mfma_f32_16x16x32_bf16 v[122:125], v[160:163], v[188:191], v[122:125]
	v_mfma_f32_16x16x32_bf16 v[106:109], v[160:163], v[196:199], v[106:109]
	v_mfma_f32_16x16x32_bf16 v[110:113], v[152:155], v[196:199], v[110:113]
	v_mfma_f32_16x16x32_bf16 v[94:97], v[152:155], v[204:207], v[94:97]
	v_mfma_f32_16x16x32_bf16 v[90:93], v[160:163], v[204:207], v[90:93]
	v_mfma_f32_16x16x32_bf16 v[74:77], v[160:163], v[212:215], v[74:77]
	v_mfma_f32_16x16x32_bf16 v[78:81], v[152:155], v[212:215], v[78:81]
	v_mfma_f32_16x16x32_bf16 v[126:129], v[156:159], v[192:195], v[126:129]
	v_mfma_f32_16x16x32_bf16 v[122:125], v[164:167], v[192:195], v[122:125]
	v_mfma_f32_16x16x32_bf16 v[106:109], v[164:167], v[200:203], v[106:109]
	v_mfma_f32_16x16x32_bf16 v[110:113], v[156:159], v[200:203], v[110:113]
	v_mfma_f32_16x16x32_bf16 v[94:97], v[156:159], v[208:211], v[94:97]
	v_mfma_f32_16x16x32_bf16 v[90:93], v[164:167], v[208:211], v[90:93]
	v_mfma_f32_16x16x32_bf16 v[74:77], v[164:167], v[216:219], v[74:77]
	v_mfma_f32_16x16x32_bf16 v[78:81], v[156:159], v[216:219], v[78:81]
	s_setprio 0
	s_setprio 1
	v_mfma_f32_16x16x32_bf16 v[118:121], v[168:171], v[188:191], v[118:121]
	v_mfma_f32_16x16x32_bf16 v[114:117], v[180:183], v[188:191], v[114:117]
	v_mfma_f32_16x16x32_bf16 v[98:101], v[180:183], v[196:199], v[98:101]
	v_mfma_f32_16x16x32_bf16 v[102:105], v[168:171], v[196:199], v[102:105]
	v_mfma_f32_16x16x32_bf16 v[86:89], v[168:171], v[204:207], v[86:89]
	v_mfma_f32_16x16x32_bf16 v[82:85], v[180:183], v[204:207], v[82:85]
	v_mfma_f32_16x16x32_bf16 v[66:69], v[180:183], v[212:215], v[66:69]
	v_mfma_f32_16x16x32_bf16 v[70:73], v[168:171], v[212:215], v[70:73]
	v_mfma_f32_16x16x32_bf16 v[118:121], v[176:179], v[192:195], v[118:121]
	v_mfma_f32_16x16x32_bf16 v[114:117], v[184:187], v[192:195], v[114:117]
	v_mfma_f32_16x16x32_bf16 v[98:101], v[184:187], v[200:203], v[98:101]
	v_mfma_f32_16x16x32_bf16 v[102:105], v[176:179], v[200:203], v[102:105]
	v_mfma_f32_16x16x32_bf16 v[86:89], v[176:179], v[208:211], v[86:89]
	v_mfma_f32_16x16x32_bf16 v[82:85], v[184:187], v[208:211], v[82:85]
	v_mfma_f32_16x16x32_bf16 v[66:69], v[184:187], v[216:219], v[66:69]
	v_mfma_f32_16x16x32_bf16 v[70:73], v[176:179], v[216:219], v[70:73]
	s_setprio 0
	s_barrier
	s_add_i32 s63, s63, s43
	v_lshl_add_u64 v[148:149], s[30:31], 0, v[134:135]
	s_mov_b32 m0, s63
	ds_read_b128 v[188:191], v151 offset:16384
	ds_read_b128 v[192:195], v151 offset:17408
	ds_read_b128 v[196:199], v151 offset:18432
	ds_read_b128 v[200:203], v151 offset:19456
	ds_read_b128 v[204:207], v151 offset:20480
	ds_read_b128 v[208:211], v151 offset:21504
	ds_read_b128 v[212:215], v151 offset:22528
	ds_read_b128 v[216:219], v151 offset:23552
	global_load_lds_dwordx4 v[148:149], off
	s_add_i32 m0, s63, 0x2000
	s_add_u32 s64, s30, 0x100000
	v_lshl_add_u64 v[172:173], s[30:31], 0, v[130:131]
	s_addc_u32 s65, s31, 0
	s_add_i32 s63, s54, s43
	global_load_lds_dwordx4 v[172:173], off
	v_lshl_add_u64 v[220:221], s[64:65], 0, v[134:135]
	s_mov_b32 m0, s63
	v_lshl_add_u64 v[222:223], s[34:35], 0, v[132:133]
	global_load_lds_dwordx4 v[220:221], off
	v_lshl_add_u64 v[220:221], s[64:65], 0, v[130:131]
	s_add_i32 m0, s63, 0x2000
	s_nop 0
	global_load_lds_dwordx4 v[220:221], off
	v_lshl_add_u64 v[220:221], s[34:35], 0, v[136:137]
	s_mov_b32 m0, s17
	s_nop 0
	global_load_lds_dwordx4 v[220:221], off
	s_mov_b32 m0, s19
	s_nop 0
	global_load_lds_dwordx4 v[222:223], off
	s_waitcnt vmcnt(8)
	s_waitcnt lgkmcnt(0)
	s_barrier
	s_setprio 1
	s_waitcnt lgkmcnt(0)
	v_mfma_f32_16x16x32_bf16 v[62:65], v[152:155], v[188:191], v[62:65]
	v_mfma_f32_16x16x32_bf16 v[58:61], v[160:163], v[188:191], v[58:61]
	v_mfma_f32_16x16x32_bf16 v[42:45], v[160:163], v[196:199], v[42:45]
	v_mfma_f32_16x16x32_bf16 v[46:49], v[152:155], v[196:199], v[46:49]
	v_mfma_f32_16x16x32_bf16 v[30:33], v[152:155], v[204:207], v[30:33]
	v_mfma_f32_16x16x32_bf16 v[26:29], v[160:163], v[204:207], v[26:29]
	v_mfma_f32_16x16x32_bf16 v[10:13], v[160:163], v[212:215], v[10:13]
	v_mfma_f32_16x16x32_bf16 v[14:17], v[152:155], v[212:215], v[14:17]
	v_mfma_f32_16x16x32_bf16 v[62:65], v[156:159], v[192:195], v[62:65]
	v_mfma_f32_16x16x32_bf16 v[58:61], v[164:167], v[192:195], v[58:61]
	v_mfma_f32_16x16x32_bf16 v[42:45], v[164:167], v[200:203], v[42:45]
	v_mfma_f32_16x16x32_bf16 v[46:49], v[156:159], v[200:203], v[46:49]
	v_mfma_f32_16x16x32_bf16 v[30:33], v[156:159], v[208:211], v[30:33]
	v_mfma_f32_16x16x32_bf16 v[26:29], v[164:167], v[208:211], v[26:29]
	v_mfma_f32_16x16x32_bf16 v[10:13], v[164:167], v[216:219], v[10:13]
	v_mfma_f32_16x16x32_bf16 v[14:17], v[156:159], v[216:219], v[14:17]
	s_setprio 0
	s_setprio 1
	v_mfma_f32_16x16x32_bf16 v[54:57], v[168:171], v[188:191], v[54:57]
	v_mfma_f32_16x16x32_bf16 v[50:53], v[180:183], v[188:191], v[50:53]
	v_mfma_f32_16x16x32_bf16 v[34:37], v[180:183], v[196:199], v[34:37]
	v_mfma_f32_16x16x32_bf16 v[38:41], v[168:171], v[196:199], v[38:41]
	v_mfma_f32_16x16x32_bf16 v[22:25], v[168:171], v[204:207], v[22:25]
	v_mfma_f32_16x16x32_bf16 v[18:21], v[180:183], v[204:207], v[18:21]
	v_mfma_f32_16x16x32_bf16 v[2:5], v[180:183], v[212:215], v[2:5]
	v_mfma_f32_16x16x32_bf16 v[6:9], v[168:171], v[212:215], v[6:9]
	v_mfma_f32_16x16x32_bf16 v[54:57], v[176:179], v[192:195], v[54:57]
	v_mfma_f32_16x16x32_bf16 v[50:53], v[184:187], v[192:195], v[50:53]
	v_mfma_f32_16x16x32_bf16 v[34:37], v[184:187], v[200:203], v[34:37]
	v_mfma_f32_16x16x32_bf16 v[38:41], v[176:179], v[200:203], v[38:41]
	v_mfma_f32_16x16x32_bf16 v[22:25], v[176:179], v[208:211], v[22:25]
	v_mfma_f32_16x16x32_bf16 v[18:21], v[184:187], v[208:211], v[18:21]
	v_mfma_f32_16x16x32_bf16 v[2:5], v[184:187], v[216:219], v[2:5]
	v_mfma_f32_16x16x32_bf16 v[6:9], v[176:179], v[216:219], v[6:9]
	s_setprio 0
	s_barrier
	s_add_i32 s63, 0, 0x18000
	s_add_i32 s64, 0, 0x1c000
	v_add_u32_e32 v164, s63, v1
	v_add_u32_e32 v175, s64, v1
	ds_read_b128 v[152:155], v164
	ds_read_b128 v[156:159], v164 offset:1024
	ds_read_b128 v[160:163], v164 offset:2048
	ds_read_b128 v[164:167], v164 offset:3072
	ds_read_b128 v[168:171], v175
	ds_read_b128 v[176:179], v175 offset:1024
	ds_read_b128 v[180:183], v175 offset:2048
	ds_read_b128 v[184:187], v175 offset:3072
	s_add_u32 s34, s34, 0x100000
	s_addc_u32 s35, s35, 0
	s_mov_b32 m0, s44
	v_lshl_add_u64 v[224:225], s[34:35], 0, v[136:137]
	ds_read_b128 v[188:191], v151 offset:32768
	ds_read_b128 v[192:195], v151 offset:33792
	ds_read_b128 v[196:199], v151 offset:34816
	ds_read_b128 v[200:203], v151 offset:35840
	ds_read_b128 v[204:207], v151 offset:36864
	ds_read_b128 v[208:211], v151 offset:37888
	ds_read_b128 v[212:215], v151 offset:38912
	ds_read_b128 v[216:219], v151 offset:39936
	global_load_lds_dwordx4 v[224:225], off
	v_lshl_add_u64 v[224:225], s[34:35], 0, v[132:133]
	s_mov_b32 m0, s45
	s_nop 0
	global_load_lds_dwordx4 v[224:225], off
	s_waitcnt vmcnt(8)
	s_waitcnt lgkmcnt(0)
	s_barrier
	s_setprio 1
	s_waitcnt lgkmcnt(0)
	v_mfma_f32_16x16x32_bf16 v[126:129], v[152:155], v[188:191], v[126:129]
	v_mfma_f32_16x16x32_bf16 v[122:125], v[160:163], v[188:191], v[122:125]
	v_mfma_f32_16x16x32_bf16 v[106:109], v[160:163], v[196:199], v[106:109]
	v_mfma_f32_16x16x32_bf16 v[110:113], v[152:155], v[196:199], v[110:113]
	v_mfma_f32_16x16x32_bf16 v[94:97], v[152:155], v[204:207], v[94:97]
	v_mfma_f32_16x16x32_bf16 v[90:93], v[160:163], v[204:207], v[90:93]
	v_mfma_f32_16x16x32_bf16 v[74:77], v[160:163], v[212:215], v[74:77]
	v_mfma_f32_16x16x32_bf16 v[78:81], v[152:155], v[212:215], v[78:81]
	v_mfma_f32_16x16x32_bf16 v[126:129], v[156:159], v[192:195], v[126:129]
	v_mfma_f32_16x16x32_bf16 v[122:125], v[164:167], v[192:195], v[122:125]
	v_mfma_f32_16x16x32_bf16 v[106:109], v[164:167], v[200:203], v[106:109]
	v_mfma_f32_16x16x32_bf16 v[110:113], v[156:159], v[200:203], v[110:113]
	v_mfma_f32_16x16x32_bf16 v[94:97], v[156:159], v[208:211], v[94:97]
	v_mfma_f32_16x16x32_bf16 v[90:93], v[164:167], v[208:211], v[90:93]
	v_mfma_f32_16x16x32_bf16 v[74:77], v[164:167], v[216:219], v[74:77]
	v_mfma_f32_16x16x32_bf16 v[78:81], v[156:159], v[216:219], v[78:81]
	s_setprio 0
	s_setprio 1
	v_mfma_f32_16x16x32_bf16 v[118:121], v[168:171], v[188:191], v[118:121]
	v_mfma_f32_16x16x32_bf16 v[114:117], v[180:183], v[188:191], v[114:117]
	v_mfma_f32_16x16x32_bf16 v[98:101], v[180:183], v[196:199], v[98:101]
	v_mfma_f32_16x16x32_bf16 v[102:105], v[168:171], v[196:199], v[102:105]
	v_mfma_f32_16x16x32_bf16 v[86:89], v[168:171], v[204:207], v[86:89]
	v_mfma_f32_16x16x32_bf16 v[82:85], v[180:183], v[204:207], v[82:85]
	v_mfma_f32_16x16x32_bf16 v[66:69], v[180:183], v[212:215], v[66:69]
	v_mfma_f32_16x16x32_bf16 v[70:73], v[168:171], v[212:215], v[70:73]
	v_mfma_f32_16x16x32_bf16 v[118:121], v[176:179], v[192:195], v[118:121]
	v_mfma_f32_16x16x32_bf16 v[114:117], v[184:187], v[192:195], v[114:117]
	v_mfma_f32_16x16x32_bf16 v[98:101], v[184:187], v[200:203], v[98:101]
	v_mfma_f32_16x16x32_bf16 v[102:105], v[176:179], v[200:203], v[102:105]
	v_mfma_f32_16x16x32_bf16 v[86:89], v[176:179], v[208:211], v[86:89]
	v_mfma_f32_16x16x32_bf16 v[82:85], v[184:187], v[208:211], v[82:85]
	v_mfma_f32_16x16x32_bf16 v[66:69], v[184:187], v[216:219], v[66:69]
	v_mfma_f32_16x16x32_bf16 v[70:73], v[176:179], v[216:219], v[70:73]
	s_setprio 0
	s_barrier
	s_add_i32 s34, s63, s43
	v_lshl_add_u64 v[148:149], v[148:149], 0, s[6:7]
	s_mov_b32 m0, s34
	ds_read_b128 v[188:191], v151 offset:49152
	ds_read_b128 v[192:195], v151 offset:50176
	ds_read_b128 v[196:199], v151 offset:51200
	ds_read_b128 v[200:203], v151 offset:52224
	ds_read_b128 v[204:207], v151 offset:53248
	ds_read_b128 v[208:211], v151 offset:54272
	ds_read_b128 v[212:215], v151 offset:55296
	ds_read_b128 v[216:219], v151 offset:56320
	global_load_lds_dwordx4 v[148:149], off
	s_add_i32 m0, s34, 0x2000
	s_add_u32 s30, s30, 0x100080
	v_lshl_add_u64 v[148:149], v[172:173], 0, s[6:7]
	s_addc_u32 s31, s31, 0
	s_add_i32 s34, s64, s43
	global_load_lds_dwordx4 v[148:149], off
	v_lshl_add_u64 v[148:149], s[30:31], 0, v[134:135]
	s_mov_b32 m0, s34
	s_nop 0
	global_load_lds_dwordx4 v[148:149], off
	v_lshl_add_u64 v[148:149], s[30:31], 0, v[130:131]
	s_add_i32 m0, s34, 0x2000
	s_nop 0
	global_load_lds_dwordx4 v[148:149], off
	v_lshl_add_u64 v[148:149], v[220:221], 0, s[6:7]
	s_mov_b32 m0, s51
	s_nop 0
	global_load_lds_dwordx4 v[148:149], off
	v_lshl_add_u64 v[148:149], v[222:223], 0, s[6:7]
	s_mov_b32 m0, s52
	s_nop 0
	global_load_lds_dwordx4 v[148:149], off
	s_waitcnt vmcnt(8)
	s_waitcnt lgkmcnt(0)
	s_barrier
	s_setprio 1
	s_waitcnt lgkmcnt(0)
	v_mfma_f32_16x16x32_bf16 v[62:65], v[152:155], v[188:191], v[62:65]
	v_mfma_f32_16x16x32_bf16 v[58:61], v[160:163], v[188:191], v[58:61]
	v_mfma_f32_16x16x32_bf16 v[42:45], v[160:163], v[196:199], v[42:45]
	v_mfma_f32_16x16x32_bf16 v[46:49], v[152:155], v[196:199], v[46:49]
	v_mfma_f32_16x16x32_bf16 v[30:33], v[152:155], v[204:207], v[30:33]
	v_mfma_f32_16x16x32_bf16 v[26:29], v[160:163], v[204:207], v[26:29]
	v_mfma_f32_16x16x32_bf16 v[10:13], v[160:163], v[212:215], v[10:13]
	v_mfma_f32_16x16x32_bf16 v[14:17], v[152:155], v[212:215], v[14:17]
	v_mfma_f32_16x16x32_bf16 v[62:65], v[156:159], v[192:195], v[62:65]
	v_mfma_f32_16x16x32_bf16 v[58:61], v[164:167], v[192:195], v[58:61]
	v_mfma_f32_16x16x32_bf16 v[42:45], v[164:167], v[200:203], v[42:45]
	v_mfma_f32_16x16x32_bf16 v[46:49], v[156:159], v[200:203], v[46:49]
	v_mfma_f32_16x16x32_bf16 v[30:33], v[156:159], v[208:211], v[30:33]
	v_mfma_f32_16x16x32_bf16 v[26:29], v[164:167], v[208:211], v[26:29]
	v_mfma_f32_16x16x32_bf16 v[10:13], v[164:167], v[216:219], v[10:13]
	v_mfma_f32_16x16x32_bf16 v[14:17], v[156:159], v[216:219], v[14:17]
	s_setprio 0
	s_setprio 1
	v_mfma_f32_16x16x32_bf16 v[54:57], v[168:171], v[188:191], v[54:57]
	v_mfma_f32_16x16x32_bf16 v[50:53], v[180:183], v[188:191], v[50:53]
	v_mfma_f32_16x16x32_bf16 v[34:37], v[180:183], v[196:199], v[34:37]
	v_mfma_f32_16x16x32_bf16 v[38:41], v[168:171], v[196:199], v[38:41]
	v_mfma_f32_16x16x32_bf16 v[22:25], v[168:171], v[204:207], v[22:25]
	v_mfma_f32_16x16x32_bf16 v[18:21], v[180:183], v[204:207], v[18:21]
	v_mfma_f32_16x16x32_bf16 v[2:5], v[180:183], v[212:215], v[2:5]
	v_mfma_f32_16x16x32_bf16 v[6:9], v[168:171], v[212:215], v[6:9]
	v_mfma_f32_16x16x32_bf16 v[54:57], v[176:179], v[192:195], v[54:57]
	v_mfma_f32_16x16x32_bf16 v[50:53], v[184:187], v[192:195], v[50:53]
	v_mfma_f32_16x16x32_bf16 v[34:37], v[184:187], v[200:203], v[34:37]
	v_mfma_f32_16x16x32_bf16 v[38:41], v[176:179], v[200:203], v[38:41]
	v_mfma_f32_16x16x32_bf16 v[22:25], v[176:179], v[208:211], v[22:25]
	v_mfma_f32_16x16x32_bf16 v[18:21], v[184:187], v[208:211], v[18:21]
	v_mfma_f32_16x16x32_bf16 v[2:5], v[184:187], v[216:219], v[2:5]
	v_mfma_f32_16x16x32_bf16 v[6:9], v[176:179], v[216:219], v[6:9]
	s_setprio 0
	s_barrier
	s_add_u32 s28, s28, 0x100
	s_addc_u32 s29, s29, 0
	s_add_u32 s60, s60, 0x100
	s_addc_u32 s61, s61, 0
	s_cmp_ge_u32 s62, s21
	s_mov_b32 s30, s62
	s_cbranch_scc0 .LBB0_595
	s_ashr_i32 s2, s2, 20
	s_cmp_gt_i32 s2, 0
	s_mov_b64 s[28:29], -1
	s_cbranch_scc0 .LBB0_598

.LBB0_731:
	ds_read_b128 v[148:151], v156
	ds_read_b128 v[160:163], v156 offset:1024
	ds_read_b128 v[164:167], v156 offset:2048
	ds_read_b128 v[168:171], v156 offset:3072
	ds_read_b128 v[176:179], v157
	ds_read_b128 v[180:183], v157 offset:1024
	ds_read_b128 v[184:187], v157 offset:2048
	ds_read_b128 v[188:191], v157 offset:3072
	s_add_u32 s22, s0, 0xfff00080
	s_addc_u32 s23, s1, -1
	s_cmp_eq_u32 s61, 60
	s_cselect_b32 s25, s5, s23
	s_cselect_b32 s24, s57, s22
	s_cselect_b32 s23, s21, s60
	s_cselect_b32 s22, s58, s59
	v_lshl_add_u64 v[152:153], s[0:1], 0, v[140:141]
	s_add_i32 m0, s34, 0xc000
	ds_read_b128 v[192:195], v158
	ds_read_b128 v[196:199], v158 offset:1024
	ds_read_b128 v[200:203], v158 offset:2048
	ds_read_b128 v[204:207], v158 offset:3072
	ds_read_b128 v[208:211], v158 offset:4096
	ds_read_b128 v[212:215], v158 offset:5120
	ds_read_b128 v[216:219], v158 offset:6144
	ds_read_b128 v[220:223], v158 offset:7168
	global_load_lds_dwordx4 v[152:153], off
	v_lshl_add_u64 v[152:153], s[0:1], 0, v[142:143]
	s_add_i32 m0, s34, 0xe000
	s_nop 0
	global_load_lds_dwordx4 v[152:153], off
	s_waitcnt vmcnt(8)
	s_waitcnt lgkmcnt(0)
	s_barrier
	s_setprio 1
	s_waitcnt lgkmcnt(0)
	v_mfma_f32_16x16x32_bf16 v[126:129], v[148:151], v[192:195], v[126:129]
	v_mfma_f32_16x16x32_bf16 v[122:125], v[164:167], v[192:195], v[122:125]
	v_mfma_f32_16x16x32_bf16 v[106:109], v[164:167], v[200:203], v[106:109]
	v_mfma_f32_16x16x32_bf16 v[110:113], v[148:151], v[200:203], v[110:113]
	v_mfma_f32_16x16x32_bf16 v[94:97], v[148:151], v[208:211], v[94:97]
	v_mfma_f32_16x16x32_bf16 v[90:93], v[164:167], v[208:211], v[90:93]
	v_mfma_f32_16x16x32_bf16 v[74:77], v[164:167], v[216:219], v[74:77]
	v_mfma_f32_16x16x32_bf16 v[78:81], v[148:151], v[216:219], v[78:81]
	v_mfma_f32_16x16x32_bf16 v[126:129], v[160:163], v[196:199], v[126:129]
	v_mfma_f32_16x16x32_bf16 v[122:125], v[168:171], v[196:199], v[122:125]
	v_mfma_f32_16x16x32_bf16 v[106:109], v[168:171], v[204:207], v[106:109]
	v_mfma_f32_16x16x32_bf16 v[110:113], v[160:163], v[204:207], v[110:113]
	v_mfma_f32_16x16x32_bf16 v[94:97], v[160:163], v[212:215], v[94:97]
	v_mfma_f32_16x16x32_bf16 v[90:93], v[168:171], v[212:215], v[90:93]
	v_mfma_f32_16x16x32_bf16 v[74:77], v[168:171], v[220:223], v[74:77]
	v_mfma_f32_16x16x32_bf16 v[78:81], v[160:163], v[220:223], v[78:81]
	s_setprio 0
	s_setprio 1
	v_mfma_f32_16x16x32_bf16 v[118:121], v[176:179], v[192:195], v[118:121]
	v_mfma_f32_16x16x32_bf16 v[114:117], v[184:187], v[192:195], v[114:117]
	v_mfma_f32_16x16x32_bf16 v[98:101], v[184:187], v[200:203], v[98:101]
	v_mfma_f32_16x16x32_bf16 v[102:105], v[176:179], v[200:203], v[102:105]
	v_mfma_f32_16x16x32_bf16 v[86:89], v[176:179], v[208:211], v[86:89]
	v_mfma_f32_16x16x32_bf16 v[82:85], v[184:187], v[208:211], v[82:85]
	v_mfma_f32_16x16x32_bf16 v[66:69], v[184:187], v[216:219], v[66:69]
	v_mfma_f32_16x16x32_bf16 v[70:73], v[176:179], v[216:219], v[70:73]
	v_mfma_f32_16x16x32_bf16 v[118:121], v[180:183], v[196:199], v[118:121]
	v_mfma_f32_16x16x32_bf16 v[114:117], v[188:191], v[196:199], v[114:117]
	v_mfma_f32_16x16x32_bf16 v[98:101], v[188:191], v[204:207], v[98:101]
	v_mfma_f32_16x16x32_bf16 v[102:105], v[180:183], v[204:207], v[102:105]
	v_mfma_f32_16x16x32_bf16 v[86:89], v[180:183], v[212:215], v[86:89]
	v_mfma_f32_16x16x32_bf16 v[82:85], v[188:191], v[212:215], v[82:85]
	v_mfma_f32_16x16x32_bf16 v[66:69], v[188:191], v[220:223], v[66:69]
	v_mfma_f32_16x16x32_bf16 v[70:73], v[180:183], v[220:223], v[70:73]
	s_setprio 0
	s_barrier
	s_add_i32 s62, s44, s31
	v_lshl_add_u64 v[152:153], s[22:23], 0, v[136:137]
	s_mov_b32 m0, s62
	ds_read_b128 v[192:195], v158 offset:16384
	ds_read_b128 v[196:199], v158 offset:17408
	ds_read_b128 v[200:203], v158 offset:18432
	ds_read_b128 v[204:207], v158 offset:19456
	ds_read_b128 v[208:211], v158 offset:20480
	ds_read_b128 v[212:215], v158 offset:21504
	ds_read_b128 v[216:219], v158 offset:22528
	ds_read_b128 v[220:223], v158 offset:23552
	global_load_lds_dwordx4 v[152:153], off
	s_add_i32 m0, s62, 0x2000
	s_add_u32 s62, s22, 0x100000
	v_lshl_add_u64 v[172:173], s[22:23], 0, v[130:131]
	s_addc_u32 s63, s23, 0
	s_add_i32 s64, s45, s31
	global_load_lds_dwordx4 v[172:173], off
	v_lshl_add_u64 v[224:225], s[62:63], 0, v[136:137]
	s_mov_b32 m0, s64
	v_lshl_add_u64 v[226:227], s[24:25], 0, v[132:133]
	global_load_lds_dwordx4 v[224:225], off
	v_lshl_add_u64 v[224:225], s[62:63], 0, v[130:131]
	s_add_i32 m0, s64, 0x2000
	s_nop 0
	global_load_lds_dwordx4 v[224:225], off
	v_lshl_add_u64 v[224:225], s[24:25], 0, v[138:139]
	s_mov_b32 m0, s34
	s_nop 0
	global_load_lds_dwordx4 v[224:225], off
	s_mov_b32 m0, s35
	s_nop 0
	global_load_lds_dwordx4 v[226:227], off
	s_waitcnt vmcnt(8)
	s_waitcnt lgkmcnt(0)
	s_barrier
	s_setprio 1
	s_waitcnt lgkmcnt(0)
	v_mfma_f32_16x16x32_bf16 v[62:65], v[148:151], v[192:195], v[62:65]
	v_mfma_f32_16x16x32_bf16 v[58:61], v[164:167], v[192:195], v[58:61]
	v_mfma_f32_16x16x32_bf16 v[42:45], v[164:167], v[200:203], v[42:45]
	v_mfma_f32_16x16x32_bf16 v[46:49], v[148:151], v[200:203], v[46:49]
	v_mfma_f32_16x16x32_bf16 v[30:33], v[148:151], v[208:211], v[30:33]
	v_mfma_f32_16x16x32_bf16 v[26:29], v[164:167], v[208:211], v[26:29]
	v_mfma_f32_16x16x32_bf16 v[10:13], v[164:167], v[216:219], v[10:13]
	v_mfma_f32_16x16x32_bf16 v[14:17], v[148:151], v[216:219], v[14:17]
	v_mfma_f32_16x16x32_bf16 v[62:65], v[160:163], v[196:199], v[62:65]
	v_mfma_f32_16x16x32_bf16 v[58:61], v[168:171], v[196:199], v[58:61]
	v_mfma_f32_16x16x32_bf16 v[42:45], v[168:171], v[204:207], v[42:45]
	v_mfma_f32_16x16x32_bf16 v[46:49], v[160:163], v[204:207], v[46:49]
	v_mfma_f32_16x16x32_bf16 v[30:33], v[160:163], v[212:215], v[30:33]
	v_mfma_f32_16x16x32_bf16 v[26:29], v[168:171], v[212:215], v[26:29]
	v_mfma_f32_16x16x32_bf16 v[10:13], v[168:171], v[220:223], v[10:13]
	v_mfma_f32_16x16x32_bf16 v[14:17], v[160:163], v[220:223], v[14:17]
	s_setprio 0
	s_setprio 1
	v_mfma_f32_16x16x32_bf16 v[54:57], v[176:179], v[192:195], v[54:57]
	v_mfma_f32_16x16x32_bf16 v[50:53], v[184:187], v[192:195], v[50:53]
	v_mfma_f32_16x16x32_bf16 v[34:37], v[184:187], v[200:203], v[34:37]
	v_mfma_f32_16x16x32_bf16 v[38:41], v[176:179], v[200:203], v[38:41]
	v_mfma_f32_16x16x32_bf16 v[22:25], v[176:179], v[208:211], v[22:25]
	v_mfma_f32_16x16x32_bf16 v[18:21], v[184:187], v[208:211], v[18:21]
	v_mfma_f32_16x16x32_bf16 v[2:5], v[184:187], v[216:219], v[2:5]
	v_mfma_f32_16x16x32_bf16 v[6:9], v[176:179], v[216:219], v[6:9]
	v_mfma_f32_16x16x32_bf16 v[54:57], v[180:183], v[196:199], v[54:57]
	v_mfma_f32_16x16x32_bf16 v[50:53], v[188:191], v[196:199], v[50:53]
	v_mfma_f32_16x16x32_bf16 v[34:37], v[188:191], v[204:207], v[34:37]
	v_mfma_f32_16x16x32_bf16 v[38:41], v[180:183], v[204:207], v[38:41]
	v_mfma_f32_16x16x32_bf16 v[22:25], v[180:183], v[212:215], v[22:25]
	v_mfma_f32_16x16x32_bf16 v[18:21], v[188:191], v[212:215], v[18:21]
	v_mfma_f32_16x16x32_bf16 v[2:5], v[188:191], v[220:223], v[2:5]
	v_mfma_f32_16x16x32_bf16 v[6:9], v[180:183], v[220:223], v[6:9]
	s_setprio 0
	s_barrier
	s_add_i32 s62, 0, 0x18000
	v_add_u32_e32 v159, s62, v135
	s_add_i32 s63, 0, 0x1c000
	ds_read_b128 v[148:151], v159
	ds_read_b128 v[160:163], v159 offset:1024
	ds_read_b128 v[164:167], v159 offset:2048
	ds_read_b128 v[168:171], v159 offset:3072
	v_add_u32_e32 v159, s63, v135
	ds_read_b128 v[176:179], v159
	ds_read_b128 v[180:183], v159 offset:1024
	ds_read_b128 v[184:187], v159 offset:2048
	ds_read_b128 v[188:191], v159 offset:3072
	s_add_u32 s24, s24, 0x100000
	s_addc_u32 s25, s25, 0
	s_mov_b32 m0, s36
	v_lshl_add_u64 v[228:229], s[24:25], 0, v[138:139]
	ds_read_b128 v[192:195], v158 offset:32768
	ds_read_b128 v[196:199], v158 offset:33792
	ds_read_b128 v[200:203], v158 offset:34816
	ds_read_b128 v[204:207], v158 offset:35840
	ds_read_b128 v[208:211], v158 offset:36864
	ds_read_b128 v[212:215], v158 offset:37888
	ds_read_b128 v[216:219], v158 offset:38912
	ds_read_b128 v[220:223], v158 offset:39936
	global_load_lds_dwordx4 v[228:229], off
	v_lshl_add_u64 v[228:229], s[24:25], 0, v[132:133]
	s_mov_b32 m0, s37
	s_nop 0
	global_load_lds_dwordx4 v[228:229], off
	s_waitcnt vmcnt(8)
	s_waitcnt lgkmcnt(0)
	s_barrier
	s_setprio 1
	s_waitcnt lgkmcnt(0)
	v_mfma_f32_16x16x32_bf16 v[126:129], v[148:151], v[192:195], v[126:129]
	v_mfma_f32_16x16x32_bf16 v[122:125], v[164:167], v[192:195], v[122:125]
	v_mfma_f32_16x16x32_bf16 v[106:109], v[164:167], v[200:203], v[106:109]
	v_mfma_f32_16x16x32_bf16 v[110:113], v[148:151], v[200:203], v[110:113]
	v_mfma_f32_16x16x32_bf16 v[94:97], v[148:151], v[208:211], v[94:97]
	v_mfma_f32_16x16x32_bf16 v[90:93], v[164:167], v[208:211], v[90:93]
	v_mfma_f32_16x16x32_bf16 v[74:77], v[164:167], v[216:219], v[74:77]
	v_mfma_f32_16x16x32_bf16 v[78:81], v[148:151], v[216:219], v[78:81]
	v_mfma_f32_16x16x32_bf16 v[126:129], v[160:163], v[196:199], v[126:129]
	v_mfma_f32_16x16x32_bf16 v[122:125], v[168:171], v[196:199], v[122:125]
	v_mfma_f32_16x16x32_bf16 v[106:109], v[168:171], v[204:207], v[106:109]
	v_mfma_f32_16x16x32_bf16 v[110:113], v[160:163], v[204:207], v[110:113]
	v_mfma_f32_16x16x32_bf16 v[94:97], v[160:163], v[212:215], v[94:97]
	v_mfma_f32_16x16x32_bf16 v[90:93], v[168:171], v[212:215], v[90:93]
	v_mfma_f32_16x16x32_bf16 v[74:77], v[168:171], v[220:223], v[74:77]
	v_mfma_f32_16x16x32_bf16 v[78:81], v[160:163], v[220:223], v[78:81]
	s_setprio 0
	s_setprio 1
	v_mfma_f32_16x16x32_bf16 v[118:121], v[176:179], v[192:195], v[118:121]
	v_mfma_f32_16x16x32_bf16 v[114:117], v[184:187], v[192:195], v[114:117]
	v_mfma_f32_16x16x32_bf16 v[98:101], v[184:187], v[200:203], v[98:101]
	v_mfma_f32_16x16x32_bf16 v[102:105], v[176:179], v[200:203], v[102:105]
	v_mfma_f32_16x16x32_bf16 v[86:89], v[176:179], v[208:211], v[86:89]
	v_mfma_f32_16x16x32_bf16 v[82:85], v[184:187], v[208:211], v[82:85]
	v_mfma_f32_16x16x32_bf16 v[66:69], v[184:187], v[216:219], v[66:69]
	v_mfma_f32_16x16x32_bf16 v[70:73], v[176:179], v[216:219], v[70:73]
	v_mfma_f32_16x16x32_bf16 v[118:121], v[180:183], v[196:199], v[118:121]
	v_mfma_f32_16x16x32_bf16 v[114:117], v[188:191], v[196:199], v[114:117]
	v_mfma_f32_16x16x32_bf16 v[98:101], v[188:191], v[204:207], v[98:101]
	v_mfma_f32_16x16x32_bf16 v[102:105], v[180:183], v[204:207], v[102:105]
	v_mfma_f32_16x16x32_bf16 v[86:89], v[180:183], v[212:215], v[86:89]
	v_mfma_f32_16x16x32_bf16 v[82:85], v[188:191], v[212:215], v[82:85]
	v_mfma_f32_16x16x32_bf16 v[66:69], v[188:191], v[220:223], v[66:69]
	v_mfma_f32_16x16x32_bf16 v[70:73], v[180:183], v[220:223], v[70:73]
	s_setprio 0
	s_barrier
	s_add_i32 s24, s62, s31
	v_lshl_add_u64 v[152:153], v[152:153], 0, s[16:17]
	s_mov_b32 m0, s24
	ds_read_b128 v[192:195], v158 offset:49152
	ds_read_b128 v[196:199], v158 offset:50176
	ds_read_b128 v[200:203], v158 offset:51200
	ds_read_b128 v[204:207], v158 offset:52224
	ds_read_b128 v[208:211], v158 offset:53248
	ds_read_b128 v[212:215], v158 offset:54272
	ds_read_b128 v[216:219], v158 offset:55296
	ds_read_b128 v[220:223], v158 offset:56320
	global_load_lds_dwordx4 v[152:153], off
	s_add_i32 m0, s24, 0x2000
	s_add_u32 s22, s22, 0x100080
	v_lshl_add_u64 v[152:153], v[172:173], 0, s[16:17]
	s_addc_u32 s23, s23, 0
	s_add_i32 s24, s63, s31
	global_load_lds_dwordx4 v[152:153], off
	v_lshl_add_u64 v[152:153], s[22:23], 0, v[136:137]
	s_mov_b32 m0, s24
	s_nop 0
	global_load_lds_dwordx4 v[152:153], off
	v_lshl_add_u64 v[152:153], s[22:23], 0, v[130:131]
	s_add_i32 m0, s24, 0x2000
	s_nop 0
	global_load_lds_dwordx4 v[152:153], off
	v_lshl_add_u64 v[152:153], v[224:225], 0, s[16:17]
	s_mov_b32 m0, s40
	s_nop 0
	global_load_lds_dwordx4 v[152:153], off
	v_lshl_add_u64 v[152:153], v[226:227], 0, s[16:17]
	s_mov_b32 m0, s41
	s_nop 0
	global_load_lds_dwordx4 v[152:153], off
	s_waitcnt vmcnt(8)
	s_waitcnt lgkmcnt(0)
	s_barrier
	s_setprio 1
	s_waitcnt lgkmcnt(0)
	v_mfma_f32_16x16x32_bf16 v[62:65], v[148:151], v[192:195], v[62:65]
	v_mfma_f32_16x16x32_bf16 v[58:61], v[164:167], v[192:195], v[58:61]
	v_mfma_f32_16x16x32_bf16 v[42:45], v[164:167], v[200:203], v[42:45]
	v_mfma_f32_16x16x32_bf16 v[46:49], v[148:151], v[200:203], v[46:49]
	v_mfma_f32_16x16x32_bf16 v[30:33], v[148:151], v[208:211], v[30:33]
	v_mfma_f32_16x16x32_bf16 v[26:29], v[164:167], v[208:211], v[26:29]
	v_mfma_f32_16x16x32_bf16 v[10:13], v[164:167], v[216:219], v[10:13]
	v_mfma_f32_16x16x32_bf16 v[14:17], v[148:151], v[216:219], v[14:17]
	v_mfma_f32_16x16x32_bf16 v[62:65], v[160:163], v[196:199], v[62:65]
	v_mfma_f32_16x16x32_bf16 v[58:61], v[168:171], v[196:199], v[58:61]
	v_mfma_f32_16x16x32_bf16 v[42:45], v[168:171], v[204:207], v[42:45]
	v_mfma_f32_16x16x32_bf16 v[46:49], v[160:163], v[204:207], v[46:49]
	v_mfma_f32_16x16x32_bf16 v[30:33], v[160:163], v[212:215], v[30:33]
	v_mfma_f32_16x16x32_bf16 v[26:29], v[168:171], v[212:215], v[26:29]
	v_mfma_f32_16x16x32_bf16 v[10:13], v[168:171], v[220:223], v[10:13]
	v_mfma_f32_16x16x32_bf16 v[14:17], v[160:163], v[220:223], v[14:17]
	s_setprio 0
	s_setprio 1
	v_mfma_f32_16x16x32_bf16 v[54:57], v[176:179], v[192:195], v[54:57]
	v_mfma_f32_16x16x32_bf16 v[50:53], v[184:187], v[192:195], v[50:53]
	v_mfma_f32_16x16x32_bf16 v[34:37], v[184:187], v[200:203], v[34:37]
	v_mfma_f32_16x16x32_bf16 v[38:41], v[176:179], v[200:203], v[38:41]
	v_mfma_f32_16x16x32_bf16 v[22:25], v[176:179], v[208:211], v[22:25]
	v_mfma_f32_16x16x32_bf16 v[18:21], v[184:187], v[208:211], v[18:21]
	v_mfma_f32_16x16x32_bf16 v[2:5], v[184:187], v[216:219], v[2:5]
	v_mfma_f32_16x16x32_bf16 v[6:9], v[176:179], v[216:219], v[6:9]
	v_mfma_f32_16x16x32_bf16 v[54:57], v[180:183], v[196:199], v[54:57]
	v_mfma_f32_16x16x32_bf16 v[50:53], v[188:191], v[196:199], v[50:53]
	v_mfma_f32_16x16x32_bf16 v[34:37], v[188:191], v[204:207], v[34:37]
	v_mfma_f32_16x16x32_bf16 v[38:41], v[180:183], v[204:207], v[38:41]
	v_mfma_f32_16x16x32_bf16 v[22:25], v[180:183], v[212:215], v[22:25]
	v_mfma_f32_16x16x32_bf16 v[18:21], v[188:191], v[212:215], v[18:21]
	v_mfma_f32_16x16x32_bf16 v[2:5], v[188:191], v[220:223], v[2:5]
	v_mfma_f32_16x16x32_bf16 v[6:9], v[180:183], v[220:223], v[6:9]
	s_setprio 0
	s_barrier
	s_add_i32 s61, s61, 2
	s_add_u32 s0, s0, 0x100
	s_addc_u32 s1, s1, 0
	s_add_u32 s59, s59, 0x100
	s_addc_u32 s60, s60, 0
	s_cmp_gt_u32 s61, 61
	s_cbranch_scc0 .LBB0_731
	v_and_b32_e32 v165, 3, v174
	v_lshrrev_b32_e32 v170, 2, v174
	v_lshlrev_b32_e32 v164, 6, v165
	v_and_or_b32 v164, v174, 60, v164
	v_and_b32_e32 v171, 15, v174
	v_sub_u32_e32 v170, v170, v171
	v_lshrrev_b32_e32 v171, 4, v174
	v_sub_u32_e32 v165, v165, v171
	v_mul_i32_i24_e32 v170, 0xac00, v170
	v_lshl_add_u32 v166, v165, 4, v170
	v_ashrrev_i32_e32 v167, 31, v166
	s_lshl_b32 s5, s56, 8
	s_add_i32 s5, s5, s39
	v_or_b32_e32 v159, s5, v1
	v_cmp_lt_i32_e64 s[0:1], s46, v159
	s_and_b64 s[22:23], s[0:1], s[18:19]
	v_mov_b64_e32 v[150:151], 0
	s_and_saveexec_b64 s[0:1], s[22:23]
	v_add_u32_e32 v148, 0xffffe000, v159
	v_lshrrev_b32_e32 v148, 2, v148
	v_and_b32_e32 v148, 0x3ffffff2, v148
	v_add_u32_e32 v150, v148, v154
	v_mov_b64_e32 v[148:149], s[10:11]
	v_mad_u64_u32 v[150:151], s[22:23], v150, s47, v[148:149]
	s_or_b64 exec, exec, s[0:1]
	v_lshl_or_b32 v148, s55, 8, v155
	v_mov_b64_e32 v[152:153], s[6:7]
	v_ashrrev_i32_e32 v149, 31, v148
	v_mad_i64_i32 v[152:153], s[0:1], v159, s48, v[152:153]
	v_lshl_add_u64 v[152:153], v[148:149], 1, v[152:153]
	v_cmp_ne_u64_e64 s[0:1], 0, v[150:151]
	v_lshl_add_u64 v[150:151], v[148:149], 2, v[150:151]
	v_cvt_pk_bf16_f32 v160, v126, v127
	v_cvt_pk_bf16_f32 v161, v128, v129
	v_cvt_pk_bf16_f32 v162, v122, v123
	v_cvt_pk_bf16_f32 v163, v124, v125
	ds_bpermute_b32 v160, v164, v160
	ds_bpermute_b32 v161, v164, v161
	ds_bpermute_b32 v162, v164, v162
	ds_bpermute_b32 v163, v164, v163
	v_lshl_add_u64 v[168:169], v[166:167], 0, v[152:153]
	s_waitcnt lgkmcnt(0)
	global_store_dwordx4 v[168:169], v[160:163], off
	s_and_saveexec_b64 s[22:23], s[0:1]
	s_cbranch_execz .LBB0_736
	global_store_dwordx4 v[150:151], v[126:129], off
	global_store_dwordx4 v[150:151], v[122:125], off offset:16

.LBB0_931:
	ds_read_b128 v[154:157], v141
	ds_read_b128 v[158:161], v141 offset:1024
	ds_read_b128 v[162:165], v141 offset:2048
	ds_read_b128 v[166:169], v141 offset:3072
	ds_read_b128 v[170:173], v152
	ds_read_b128 v[176:179], v152 offset:1024
	ds_read_b128 v[180:183], v152 offset:2048
	ds_read_b128 v[184:187], v152 offset:3072
	s_add_i32 s73, s24, 2
	s_add_u32 s25, s22, 0xffd50080
	s_addc_u32 s26, s23, -1
	s_cmp_eq_u32 s70, s24
	s_cselect_b32 s24, s20, s71
	s_cselect_b32 s27, s17, s26
	s_cselect_b32 s26, s16, s25
	s_cselect_b32 s25, s21, s72
	v_lshl_add_u64 v[150:151], s[22:23], 0, v[144:145]
	s_add_i32 m0, s38, 0xc000
	ds_read_b128 v[188:191], v153
	ds_read_b128 v[192:195], v153 offset:1024
	ds_read_b128 v[196:199], v153 offset:2048
	ds_read_b128 v[200:203], v153 offset:3072
	ds_read_b128 v[204:207], v153 offset:4096
	ds_read_b128 v[208:211], v153 offset:5120
	ds_read_b128 v[212:215], v153 offset:6144
	ds_read_b128 v[216:219], v153 offset:7168
	global_load_lds_dwordx4 v[150:151], off
	v_lshl_add_u64 v[150:151], s[22:23], 0, v[146:147]
	s_add_i32 m0, s38, 0xe000
	s_nop 0
	global_load_lds_dwordx4 v[150:151], off
	s_waitcnt vmcnt(8)
	s_waitcnt lgkmcnt(0)
	s_barrier
	s_setprio 1
	s_waitcnt lgkmcnt(0)
	v_mfma_f32_16x16x32_bf16 v[126:129], v[154:157], v[188:191], v[126:129]
	v_mfma_f32_16x16x32_bf16 v[122:125], v[162:165], v[188:191], v[122:125]
	v_mfma_f32_16x16x32_bf16 v[106:109], v[162:165], v[196:199], v[106:109]
	v_mfma_f32_16x16x32_bf16 v[110:113], v[154:157], v[196:199], v[110:113]
	v_mfma_f32_16x16x32_bf16 v[94:97], v[154:157], v[204:207], v[94:97]
	v_mfma_f32_16x16x32_bf16 v[90:93], v[162:165], v[204:207], v[90:93]
	v_mfma_f32_16x16x32_bf16 v[74:77], v[162:165], v[212:215], v[74:77]
	v_mfma_f32_16x16x32_bf16 v[78:81], v[154:157], v[212:215], v[78:81]
	v_mfma_f32_16x16x32_bf16 v[126:129], v[158:161], v[192:195], v[126:129]
	v_mfma_f32_16x16x32_bf16 v[122:125], v[166:169], v[192:195], v[122:125]
	v_mfma_f32_16x16x32_bf16 v[106:109], v[166:169], v[200:203], v[106:109]
	v_mfma_f32_16x16x32_bf16 v[110:113], v[158:161], v[200:203], v[110:113]
	v_mfma_f32_16x16x32_bf16 v[94:97], v[158:161], v[208:211], v[94:97]
	v_mfma_f32_16x16x32_bf16 v[90:93], v[166:169], v[208:211], v[90:93]
	v_mfma_f32_16x16x32_bf16 v[74:77], v[166:169], v[216:219], v[74:77]
	v_mfma_f32_16x16x32_bf16 v[78:81], v[158:161], v[216:219], v[78:81]
	s_setprio 0
	s_setprio 1
	v_mfma_f32_16x16x32_bf16 v[118:121], v[170:173], v[188:191], v[118:121]
	v_mfma_f32_16x16x32_bf16 v[114:117], v[180:183], v[188:191], v[114:117]
	v_mfma_f32_16x16x32_bf16 v[98:101], v[180:183], v[196:199], v[98:101]
	v_mfma_f32_16x16x32_bf16 v[102:105], v[170:173], v[196:199], v[102:105]
	v_mfma_f32_16x16x32_bf16 v[86:89], v[170:173], v[204:207], v[86:89]
	v_mfma_f32_16x16x32_bf16 v[82:85], v[180:183], v[204:207], v[82:85]
	v_mfma_f32_16x16x32_bf16 v[66:69], v[180:183], v[212:215], v[66:69]
	v_mfma_f32_16x16x32_bf16 v[70:73], v[170:173], v[212:215], v[70:73]
	v_mfma_f32_16x16x32_bf16 v[118:121], v[176:179], v[192:195], v[118:121]
	v_mfma_f32_16x16x32_bf16 v[114:117], v[184:187], v[192:195], v[114:117]
	v_mfma_f32_16x16x32_bf16 v[98:101], v[184:187], v[200:203], v[98:101]
	v_mfma_f32_16x16x32_bf16 v[102:105], v[176:179], v[200:203], v[102:105]
	v_mfma_f32_16x16x32_bf16 v[86:89], v[176:179], v[208:211], v[86:89]
	v_mfma_f32_16x16x32_bf16 v[82:85], v[184:187], v[208:211], v[82:85]
	v_mfma_f32_16x16x32_bf16 v[66:69], v[184:187], v[216:219], v[66:69]
	v_mfma_f32_16x16x32_bf16 v[70:73], v[176:179], v[216:219], v[70:73]
	s_setprio 0
	s_barrier
	s_add_i32 s74, s57, s37
	v_lshl_add_u64 v[150:151], s[24:25], 0, v[136:137]
	s_mov_b32 m0, s74
	ds_read_b128 v[188:191], v153 offset:16384
	ds_read_b128 v[192:195], v153 offset:17408
	ds_read_b128 v[196:199], v153 offset:18432
	ds_read_b128 v[200:203], v153 offset:19456
	ds_read_b128 v[204:207], v153 offset:20480
	ds_read_b128 v[208:211], v153 offset:21504
	ds_read_b128 v[212:215], v153 offset:22528
	ds_read_b128 v[216:219], v153 offset:23552
	global_load_lds_dwordx4 v[150:151], off
	s_add_i32 m0, s74, 0x2000
	s_add_u32 s74, s24, 0x2b0000
	v_lshl_add_u64 v[220:221], s[24:25], 0, v[130:131]
	s_addc_u32 s75, s25, 0
	s_add_i32 s76, s58, s37
	global_load_lds_dwordx4 v[220:221], off
	v_lshl_add_u64 v[222:223], s[74:75], 0, v[136:137]
	s_mov_b32 m0, s76
	v_lshl_add_u64 v[224:225], s[26:27], 0, v[132:133]
	global_load_lds_dwordx4 v[222:223], off
	v_lshl_add_u64 v[222:223], s[74:75], 0, v[130:131]
	s_add_i32 m0, s76, 0x2000
	s_nop 0
	global_load_lds_dwordx4 v[222:223], off
	v_lshl_add_u64 v[222:223], s[26:27], 0, v[138:139]
	s_mov_b32 m0, s38
	s_nop 0
	global_load_lds_dwordx4 v[222:223], off
	s_mov_b32 m0, s39
	s_nop 0
	global_load_lds_dwordx4 v[224:225], off
	s_waitcnt vmcnt(8)
	s_waitcnt lgkmcnt(0)
	s_barrier
	s_setprio 1
	s_waitcnt lgkmcnt(0)
	v_mfma_f32_16x16x32_bf16 v[62:65], v[154:157], v[188:191], v[62:65]
	v_mfma_f32_16x16x32_bf16 v[58:61], v[162:165], v[188:191], v[58:61]
	v_mfma_f32_16x16x32_bf16 v[42:45], v[162:165], v[196:199], v[42:45]
	v_mfma_f32_16x16x32_bf16 v[46:49], v[154:157], v[196:199], v[46:49]
	v_mfma_f32_16x16x32_bf16 v[30:33], v[154:157], v[204:207], v[30:33]
	v_mfma_f32_16x16x32_bf16 v[26:29], v[162:165], v[204:207], v[26:29]
	v_mfma_f32_16x16x32_bf16 v[10:13], v[162:165], v[212:215], v[10:13]
	v_mfma_f32_16x16x32_bf16 v[14:17], v[154:157], v[212:215], v[14:17]
	v_mfma_f32_16x16x32_bf16 v[62:65], v[158:161], v[192:195], v[62:65]
	v_mfma_f32_16x16x32_bf16 v[58:61], v[166:169], v[192:195], v[58:61]
	v_mfma_f32_16x16x32_bf16 v[42:45], v[166:169], v[200:203], v[42:45]
	v_mfma_f32_16x16x32_bf16 v[46:49], v[158:161], v[200:203], v[46:49]
	v_mfma_f32_16x16x32_bf16 v[30:33], v[158:161], v[208:211], v[30:33]
	v_mfma_f32_16x16x32_bf16 v[26:29], v[166:169], v[208:211], v[26:29]
	v_mfma_f32_16x16x32_bf16 v[10:13], v[166:169], v[216:219], v[10:13]
	v_mfma_f32_16x16x32_bf16 v[14:17], v[158:161], v[216:219], v[14:17]
	s_setprio 0
	s_setprio 1
	v_mfma_f32_16x16x32_bf16 v[54:57], v[170:173], v[188:191], v[54:57]
	v_mfma_f32_16x16x32_bf16 v[50:53], v[180:183], v[188:191], v[50:53]
	v_mfma_f32_16x16x32_bf16 v[34:37], v[180:183], v[196:199], v[34:37]
	v_mfma_f32_16x16x32_bf16 v[38:41], v[170:173], v[196:199], v[38:41]
	v_mfma_f32_16x16x32_bf16 v[22:25], v[170:173], v[204:207], v[22:25]
	v_mfma_f32_16x16x32_bf16 v[18:21], v[180:183], v[204:207], v[18:21]
	v_mfma_f32_16x16x32_bf16 v[2:5], v[180:183], v[212:215], v[2:5]
	v_mfma_f32_16x16x32_bf16 v[6:9], v[170:173], v[212:215], v[6:9]
	v_mfma_f32_16x16x32_bf16 v[54:57], v[176:179], v[192:195], v[54:57]
	v_mfma_f32_16x16x32_bf16 v[50:53], v[184:187], v[192:195], v[50:53]
	v_mfma_f32_16x16x32_bf16 v[34:37], v[184:187], v[200:203], v[34:37]
	v_mfma_f32_16x16x32_bf16 v[38:41], v[176:179], v[200:203], v[38:41]
	v_mfma_f32_16x16x32_bf16 v[22:25], v[176:179], v[208:211], v[22:25]
	v_mfma_f32_16x16x32_bf16 v[18:21], v[184:187], v[208:211], v[18:21]
	v_mfma_f32_16x16x32_bf16 v[2:5], v[184:187], v[216:219], v[2:5]
	v_mfma_f32_16x16x32_bf16 v[6:9], v[176:179], v[216:219], v[6:9]
	s_setprio 0
	s_barrier
	s_add_i32 s74, 0, 0x18000
	s_add_i32 s75, 0, 0x1c000
	v_add_u32_e32 v166, s74, v1
	v_add_u32_e32 v175, s75, v1
	ds_read_b128 v[154:157], v166
	ds_read_b128 v[158:161], v166 offset:1024
	ds_read_b128 v[162:165], v166 offset:2048
	ds_read_b128 v[166:169], v166 offset:3072
	ds_read_b128 v[170:173], v175
	ds_read_b128 v[176:179], v175 offset:1024
	ds_read_b128 v[180:183], v175 offset:2048
	ds_read_b128 v[184:187], v175 offset:3072
	s_add_u32 s26, s26, 0x2b0000
	s_addc_u32 s27, s27, 0
	s_mov_b32 m0, s40
	v_lshl_add_u64 v[226:227], s[26:27], 0, v[138:139]
	ds_read_b128 v[188:191], v153 offset:32768
	ds_read_b128 v[192:195], v153 offset:33792
	ds_read_b128 v[196:199], v153 offset:34816
	ds_read_b128 v[200:203], v153 offset:35840
	ds_read_b128 v[204:207], v153 offset:36864
	ds_read_b128 v[208:211], v153 offset:37888
	ds_read_b128 v[212:215], v153 offset:38912
	ds_read_b128 v[216:219], v153 offset:39936
	global_load_lds_dwordx4 v[226:227], off
	v_lshl_add_u64 v[226:227], s[26:27], 0, v[132:133]
	s_mov_b32 m0, s41
	s_nop 0
	global_load_lds_dwordx4 v[226:227], off
	s_waitcnt vmcnt(8)
	s_waitcnt lgkmcnt(0)
	s_barrier
	s_setprio 1
	s_waitcnt lgkmcnt(0)
	v_mfma_f32_16x16x32_bf16 v[126:129], v[154:157], v[188:191], v[126:129]
	v_mfma_f32_16x16x32_bf16 v[122:125], v[162:165], v[188:191], v[122:125]
	v_mfma_f32_16x16x32_bf16 v[106:109], v[162:165], v[196:199], v[106:109]
	v_mfma_f32_16x16x32_bf16 v[110:113], v[154:157], v[196:199], v[110:113]
	v_mfma_f32_16x16x32_bf16 v[94:97], v[154:157], v[204:207], v[94:97]
	v_mfma_f32_16x16x32_bf16 v[90:93], v[162:165], v[204:207], v[90:93]
	v_mfma_f32_16x16x32_bf16 v[74:77], v[162:165], v[212:215], v[74:77]
	v_mfma_f32_16x16x32_bf16 v[78:81], v[154:157], v[212:215], v[78:81]
	v_mfma_f32_16x16x32_bf16 v[126:129], v[158:161], v[192:195], v[126:129]
	v_mfma_f32_16x16x32_bf16 v[122:125], v[166:169], v[192:195], v[122:125]
	v_mfma_f32_16x16x32_bf16 v[106:109], v[166:169], v[200:203], v[106:109]
	v_mfma_f32_16x16x32_bf16 v[110:113], v[158:161], v[200:203], v[110:113]
	v_mfma_f32_16x16x32_bf16 v[94:97], v[158:161], v[208:211], v[94:97]
	v_mfma_f32_16x16x32_bf16 v[90:93], v[166:169], v[208:211], v[90:93]
	v_mfma_f32_16x16x32_bf16 v[74:77], v[166:169], v[216:219], v[74:77]
	v_mfma_f32_16x16x32_bf16 v[78:81], v[158:161], v[216:219], v[78:81]
	s_setprio 0
	s_setprio 1
	v_mfma_f32_16x16x32_bf16 v[118:121], v[170:173], v[188:191], v[118:121]
	v_mfma_f32_16x16x32_bf16 v[114:117], v[180:183], v[188:191], v[114:117]
	v_mfma_f32_16x16x32_bf16 v[98:101], v[180:183], v[196:199], v[98:101]
	v_mfma_f32_16x16x32_bf16 v[102:105], v[170:173], v[196:199], v[102:105]
	v_mfma_f32_16x16x32_bf16 v[86:89], v[170:173], v[204:207], v[86:89]
	v_mfma_f32_16x16x32_bf16 v[82:85], v[180:183], v[204:207], v[82:85]
	v_mfma_f32_16x16x32_bf16 v[66:69], v[180:183], v[212:215], v[66:69]
	v_mfma_f32_16x16x32_bf16 v[70:73], v[170:173], v[212:215], v[70:73]
	v_mfma_f32_16x16x32_bf16 v[118:121], v[176:179], v[192:195], v[118:121]
	v_mfma_f32_16x16x32_bf16 v[114:117], v[184:187], v[192:195], v[114:117]
	v_mfma_f32_16x16x32_bf16 v[98:101], v[184:187], v[200:203], v[98:101]
	v_mfma_f32_16x16x32_bf16 v[102:105], v[176:179], v[200:203], v[102:105]
	v_mfma_f32_16x16x32_bf16 v[86:89], v[176:179], v[208:211], v[86:89]
	v_mfma_f32_16x16x32_bf16 v[82:85], v[184:187], v[208:211], v[82:85]
	v_mfma_f32_16x16x32_bf16 v[66:69], v[184:187], v[216:219], v[66:69]
	v_mfma_f32_16x16x32_bf16 v[70:73], v[176:179], v[216:219], v[70:73]
	s_setprio 0
	s_barrier
	s_add_i32 s26, s74, s37
	v_lshl_add_u64 v[150:151], v[150:151], 0, s[6:7]
	s_mov_b32 m0, s26
	ds_read_b128 v[188:191], v153 offset:49152
	ds_read_b128 v[192:195], v153 offset:50176
	ds_read_b128 v[196:199], v153 offset:51200
	ds_read_b128 v[200:203], v153 offset:52224
	ds_read_b128 v[204:207], v153 offset:53248
	ds_read_b128 v[208:211], v153 offset:54272
	ds_read_b128 v[212:215], v153 offset:55296
	ds_read_b128 v[216:219], v153 offset:56320
	global_load_lds_dwordx4 v[150:151], off
	s_add_i32 m0, s26, 0x2000
	s_add_u32 s24, s24, 0x2b0080
	v_lshl_add_u64 v[150:151], v[220:221], 0, s[6:7]
	s_addc_u32 s25, s25, 0
	s_add_i32 s26, s75, s37
	global_load_lds_dwordx4 v[150:151], off
	v_lshl_add_u64 v[150:151], s[24:25], 0, v[136:137]
	s_mov_b32 m0, s26
	s_nop 0
	global_load_lds_dwordx4 v[150:151], off
	v_lshl_add_u64 v[150:151], s[24:25], 0, v[130:131]
	s_add_i32 m0, s26, 0x2000
	s_nop 0
	global_load_lds_dwordx4 v[150:151], off
	v_lshl_add_u64 v[150:151], v[222:223], 0, s[6:7]
	s_mov_b32 m0, s54
	s_nop 0
	global_load_lds_dwordx4 v[150:151], off
	v_lshl_add_u64 v[150:151], v[224:225], 0, s[6:7]
	s_mov_b32 m0, s55
	s_nop 0
	global_load_lds_dwordx4 v[150:151], off
	s_waitcnt vmcnt(8)
	s_waitcnt lgkmcnt(0)
	s_barrier
	s_setprio 1
	s_waitcnt lgkmcnt(0)
	v_mfma_f32_16x16x32_bf16 v[62:65], v[154:157], v[188:191], v[62:65]
	v_mfma_f32_16x16x32_bf16 v[58:61], v[162:165], v[188:191], v[58:61]
	v_mfma_f32_16x16x32_bf16 v[42:45], v[162:165], v[196:199], v[42:45]
	v_mfma_f32_16x16x32_bf16 v[46:49], v[154:157], v[196:199], v[46:49]
	v_mfma_f32_16x16x32_bf16 v[30:33], v[154:157], v[204:207], v[30:33]
	v_mfma_f32_16x16x32_bf16 v[26:29], v[162:165], v[204:207], v[26:29]
	v_mfma_f32_16x16x32_bf16 v[10:13], v[162:165], v[212:215], v[10:13]
	v_mfma_f32_16x16x32_bf16 v[14:17], v[154:157], v[212:215], v[14:17]
	v_mfma_f32_16x16x32_bf16 v[62:65], v[158:161], v[192:195], v[62:65]
	v_mfma_f32_16x16x32_bf16 v[58:61], v[166:169], v[192:195], v[58:61]
	v_mfma_f32_16x16x32_bf16 v[42:45], v[166:169], v[200:203], v[42:45]
	v_mfma_f32_16x16x32_bf16 v[46:49], v[158:161], v[200:203], v[46:49]
	v_mfma_f32_16x16x32_bf16 v[30:33], v[158:161], v[208:211], v[30:33]
	v_mfma_f32_16x16x32_bf16 v[26:29], v[166:169], v[208:211], v[26:29]
	v_mfma_f32_16x16x32_bf16 v[10:13], v[166:169], v[216:219], v[10:13]
	v_mfma_f32_16x16x32_bf16 v[14:17], v[158:161], v[216:219], v[14:17]
	s_setprio 0
	s_setprio 1
	v_mfma_f32_16x16x32_bf16 v[54:57], v[170:173], v[188:191], v[54:57]
	v_mfma_f32_16x16x32_bf16 v[50:53], v[180:183], v[188:191], v[50:53]
	v_mfma_f32_16x16x32_bf16 v[34:37], v[180:183], v[196:199], v[34:37]
	v_mfma_f32_16x16x32_bf16 v[38:41], v[170:173], v[196:199], v[38:41]
	v_mfma_f32_16x16x32_bf16 v[22:25], v[170:173], v[204:207], v[22:25]
	v_mfma_f32_16x16x32_bf16 v[18:21], v[180:183], v[204:207], v[18:21]
	v_mfma_f32_16x16x32_bf16 v[2:5], v[180:183], v[212:215], v[2:5]
	v_mfma_f32_16x16x32_bf16 v[6:9], v[170:173], v[212:215], v[6:9]
	v_mfma_f32_16x16x32_bf16 v[54:57], v[176:179], v[192:195], v[54:57]
	v_mfma_f32_16x16x32_bf16 v[50:53], v[184:187], v[192:195], v[50:53]
	v_mfma_f32_16x16x32_bf16 v[34:37], v[184:187], v[200:203], v[34:37]
	v_mfma_f32_16x16x32_bf16 v[38:41], v[176:179], v[200:203], v[38:41]
	v_mfma_f32_16x16x32_bf16 v[22:25], v[176:179], v[208:211], v[22:25]
	v_mfma_f32_16x16x32_bf16 v[18:21], v[184:187], v[208:211], v[18:21]
	v_mfma_f32_16x16x32_bf16 v[2:5], v[184:187], v[216:219], v[2:5]
	v_mfma_f32_16x16x32_bf16 v[6:9], v[176:179], v[216:219], v[6:9]
	s_setprio 0
	s_barrier
	s_add_u32 s22, s22, 0x100
	s_addc_u32 s23, s23, 0
	s_add_u32 s71, s71, 0x100
	s_addc_u32 s72, s72, 0
	s_cmp_ge_u32 s73, s2
	s_mov_b32 s24, s73
	s_cbranch_scc0 .LBB0_931
	s_ashr_i32 s2, s69, 20
	s_cmp_gt_i32 s2, 0
	s_mov_b64 s[22:23], -1
	s_cbranch_scc0 .LBB0_934
